# v66 plus WIN rows 3584.. (conv/gate columns) of each layer converted inside that layer's scan; hipcc converter's WIN job limited to rows 0..3583
# speedup vs baseline: 1.0153x; 1.0068x over previous
.LBB0_96:
	s_lshr_b32 s10, s13, 6
	s_waitcnt vmcnt(0)
	v_cvt_f32_ubyte0_e32 v0, s10
	s_lshr_b32 s4, s14, 6
	v_rcp_iflag_f32_e32 v35, v0
	s_mul_i32 s11, s10, s4
	s_cmp_eq_u32 s12, 2
	s_cselect_b32 s11, 0x380, s11
	s_cmp_lt_i32 s2, s11
	v_mov_b32_e32 v34, v241
	s_cselect_b64 s[34:35], -1, 0
	s_cmp_ge_i32 s2, s11
	s_cbranch_scc1 .LBB0_163
	v_mul_f32_e32 v0, 0x4f7ffffe, v35
	v_cvt_u32_f32_e32 v0, v0
	s_sub_i32 s4, 0, s10
	v_readlane_b32 s7, v254, 19
	v_readfirstlane_b32 s15, v0
	s_mul_i32 s4, s4, s15
	s_mul_hi_u32 s4, s15, s4
	s_add_i32 s15, s15, s4
	s_mul_hi_u32 s4, s7, s15
	s_mul_i32 s5, s4, s10
	s_sub_i32 s5, s7, s5
	s_add_i32 s6, s4, 1
	s_sub_i32 s7, s5, s10
	s_cmp_ge_u32 s5, s10
	s_cselect_b32 s4, s6, s4
	s_cselect_b32 s5, s7, s5
	s_add_i32 s6, s4, 1
	s_cmp_ge_u32 s5, s10
	s_cselect_b32 s4, s6, s4
	s_xor_b32 s4, s4, s3
	s_sub_i32 s5, s4, s3
	s_lshl_b32 s4, s5, 6
	s_cmp_lt_i32 s12, 1
	s_cbranch_scc1 .LBB0_112
	s_cmp_lg_u32 s12, 1
	s_mov_b64 s[6:7], -1
	s_cbranch_scc0 .LBB0_109
	s_cmpk_lt_i32 s4, 0xd00
	s_mov_b32 s38, s4
	s_cbranch_scc1 .LBB0_108
	s_add_i32 s39, s4, 0xfffff300
	s_and_b32 s40, s4, 0xc0
	s_cmpk_gt_u32 s39, 0x3ff
	s_cbranch_scc0 .LBB0_106
	s_lshr_b32 s6, s39, 1
	s_and_b32 s41, s4, 64
	s_and_b32 s42, s6, 0x7fffff80
	s_cmpk_lt_u32 s40, 0x80
	s_cselect_b64 s[6:7], -1, 0
	s_cmpk_gt_u32 s39, 0xbff
	s_mov_b64 s[8:9], -1
	s_cbranch_scc0 .LBB0_103
	s_and_b64 s[8:9], s[6:7], exec
	s_movk_i32 s8, 0x1100
	s_cselect_b32 s8, s8, 0x1500
	s_add_i32 s9, s42, s41
	s_add_i32 s8, s9, s8
	s_add_i32 s38, s8, 0xfffffa00
	s_mov_b64 s[8:9], 0

.Lcv_noproc:
	s_mov_b32 s34, 0
	s_sub_u32 s54, s12, 18
	s_cmp_lt_u32 s54, 0x40
	s_cbranch_scc0 .Lcv_noitem
	s_lshl_b32 s54, s54, 10
	s_lshl_b32 s53, s8, 2
	s_add_i32 s53, s53, s11
	s_add_i32 s53, s53, -4
	s_add_i32 s54, s54, s53
	s_mov_b32 s55, 0x3800
	s_cmp_eq_u32 s30, 0
	s_cselect_b32 s55, 0x5900, s55
	s_cmp_lt_u32 s54, s55
	s_cbranch_scc0 .Lcv_noitem
	s_lshl_b32 s61, s30, 12
	s_cmp_lt_u32 s54, 0x1300
	s_cbranch_scc0 .Lcv_j1
	v_readlane_b32 s58, v254, 55
	v_readlane_b32 s59, v254, 56
	v_readlane_b32 s6, v254, 53
	v_readlane_b32 s7, v254, 54
	s_mul_i32 s4, s30, 0x2100000
	s_mov_b32 s60, 0x1080000
	s_mov_b32 s57, 3
	s_nop 1
	s_add_u32 s6, s6, s61
	s_addc_u32 s7, s7, 0
	s_branch .Lcv_jsel
.Lcv_j1:
	s_cmp_lt_u32 s54, 0x1700
	s_cbranch_scc0 .Lcv_j2
	s_sub_u32 s54, s54, 0x1300
	v_readlane_b32 s58, v255, 17
	v_readlane_b32 s59, v255, 18
	s_lshl_b32 s4, s30, 22
	s_mov_b32 s60, 0x2100000
	s_mov_b32 s57, 0
	s_branch .Lcv_jsel
.Lcv_j2:
	s_cmp_lt_u32 s54, 0x2d00
	s_cbranch_scc0 .Lcv_j3
	s_sub_u32 s54, s54, 0x1700
	s_mov_b64 s[58:59], s[22:23]
	s_mul_i32 s4, s30, 0x1600000
	s_add_u32 s6, s20, s61
	s_addc_u32 s7, s21, 0
	s_mov_b32 s60, 0x2300000
	s_mov_b32 s57, 1
	s_branch .Lcv_jsel
.Lcv_j3:
	s_cmp_lt_u32 s54, 0x3800
	s_cbranch_scc0 .Lcv_j4
	s_sub_u32 s54, s54, 0x2d00
	s_mov_b64 s[58:59], s[24:25]
	s_mul_i32 s4, s30, 0xb00000
	s_mov_b32 s60, 0x2e00000
	s_mov_b32 s57, 2
	s_branch .Lcv_jsel
.Lcv_j4:
	s_cmp_lt_u32 s54, 0x4e00
	s_cbranch_scc0 .Lcv_j5
	s_sub_u32 s54, s54, 0x3800
	v_readlane_b32 s58, v254, 49
	v_readlane_b32 s59, v254, 50
	v_readlane_b32 s6, v254, 47
	v_readlane_b32 s7, v254, 48
	s_mov_b32 s4, 0x1600000
	s_mov_b32 s60, 0
	s_mov_b32 s57, 1
	s_nop 1
	s_add_u32 s6, s6, 0x1000
	s_addc_u32 s7, s7, 0
	s_branch .Lcv_jsel
.Lcv_j5:
	s_sub_u32 s54, s54, 0x4e00
	v_readlane_b32 s58, v254, 51
	v_readlane_b32 s59, v254, 52
	s_mov_b32 s4, 0xb00000
	s_mov_b32 s60, 0xb00000
	s_mov_b32 s57, 2

.Lcv_shd:
	s_lshr_b32 s56, s54, 4
	s_mul_i32 s56, s56, 0xd795
	s_lshr_b32 s56, s56, 20
	s_mul_i32 s55, s56, 0x130
	s_sub_u32 s55, s54, s55
	s_add_i32 s55, s55, 0xe0
	s_lshl_b32 s0, s55, 4
	s_sub_u32 s1, s0, 0xd00
	s_lshr_b32 s4, s1, 8
	s_and_b32 s5, s1, 0xff
	s_cmp_lt_u32 s4, 4
	s_cbranch_scc0 .Lcv_m2b
	s_lshl_b32 s0, s4, 8
	s_add_i32 s0, s0, s5
	s_add_i32 s0, s0, 0x1900
	s_branch .Lcv_m2done

.LBB0_606:
	s_and_b64 vcc, exec, s[0:1]
	s_cbranch_vccz .LBB0_508
	s_waitcnt vmcnt(0)
	v_lshrrev_b32_e32 v90, 4, v241
	v_bfe_u32 v91, v241, 3, 1
	v_and_b32_e32 v86, 15, v241
	v_lshlrev_b32_e32 v90, 1, v90
	v_lshlrev_b32_e32 v86, 4, v86
	v_add_u32_e32 v92, v90, v91
	v_xor_b32_e32 v91, 1, v91
	v_add_u32_e32 v93, v90, v91
	s_lshl_b32 s0, s10, 5
	v_lshlrev_b32_e32 v89, 2, v92
	v_add_u32_e32 v92, s0, v92
	v_add_u32_e32 v93, s0, v93
	v_add_u32_e32 v89, 0x18000, v89
	v_lshlrev_b32_e32 v87, 2, v92
	v_lshlrev_b32_e32 v88, 2, v93
	v_mov_b32_e32 v0, 0
	v_mov_b32_e32 v1, 0
	v_mov_b32_e32 v2, 0
	v_mov_b32_e32 v3, 0
	v_mov_b32_e32 v4, 0
	v_mov_b32_e32 v5, 0
	v_mov_b32_e32 v6, 0
	v_mov_b32_e32 v7, 0
	s_waitcnt lgkmcnt(0)
	s_barrier
	s_mov_b32 s4, 0
	s_nop 0
.Lrec_chunk:
	s_and_b32 s0, s4, 1
	s_mul_i32 s1, s0, 0xc000
	s_lshl_b32 s5, s0, 8
	v_add_u32_e32 v80, s1, v86
	v_add_u32_e32 v81, s1, v87
	v_add_u32_e32 v82, s1, v88
	s_add_i32 s5, s5, 0x1a100
	s_lshl_b32 s0, s0, 12
	v_mov_b32_e32 v83, s5
	v_add_u32_e32 v84, s0, v89
	ds_read_b128 v[12:15], v80 offset:768
	ds_read_b128 v[16:19], v80 offset:0
	ds_read_b128 v[20:23], v80 offset:256
	ds_read_b128 v[24:27], v80 offset:512
	ds_read_b128 v[28:31], v80 offset:1024
	ds_read_b32 v32, v81 offset:1280
	ds_read_b32 v33, v82 offset:1280
	s_waitcnt lgkmcnt(5)
	v_pk_mul_f32 v[8:9], v[0:1], v[12:13] op_sel_hi:[1,0]
	v_pk_mul_f32 v[10:11], v[0:1], v[16:17] op_sel_hi:[1,0]
	ds_read_b128 v[40:43], v80 offset:2304
	v_pk_fma_f32 v[8:9], v[2:3], v[12:13], v[8:9] op_sel:[0,1,0]
	v_pk_fma_f32 v[10:11], v[2:3], v[16:17], v[10:11] op_sel:[0,1,0]
	ds_read_b128 v[44:47], v80 offset:1536
	v_pk_fma_f32 v[8:9], v[4:5], v[14:15], v[8:9] op_sel_hi:[1,0,1]
	v_pk_fma_f32 v[10:11], v[4:5], v[18:19], v[10:11] op_sel_hi:[1,0,1]
	ds_read_b128 v[48:51], v80 offset:1792
	v_pk_fma_f32 v[8:9], v[6:7], v[14:15], v[8:9] op_sel:[0,1,0]
	v_pk_fma_f32 v[10:11], v[6:7], v[18:19], v[10:11] op_sel:[0,1,0]
	ds_read_b128 v[52:55], v80 offset:2048
	v_add_f32_dpp v74, v9, v8 row_ror:8 row_mask:0xf bank_mask:0xf bound_ctrl:1
	v_add_f32_dpp v75, v11, v10 row_ror:8 row_mask:0xf bank_mask:0xf bound_ctrl:1
	ds_read_b128 v[56:59], v80 offset:2560
	v_add_f32_dpp v74, v74, v74 quad_perm:[1,0,3,2] row_mask:0xf bank_mask:0xf bound_ctrl:1
	v_add_f32_dpp v75, v75, v75 quad_perm:[1,0,3,2] row_mask:0xf bank_mask:0xf bound_ctrl:1
	ds_read_b32 v60, v81 offset:2816
	v_add_f32_dpp v74, v74, v74 quad_perm:[2,3,0,1] row_mask:0xf bank_mask:0xf bound_ctrl:1
	v_add_f32_dpp v75, v75, v75 quad_perm:[2,3,0,1] row_mask:0xf bank_mask:0xf bound_ctrl:1
	ds_read_b32 v61, v82 offset:2816
	v_add_f32_dpp v76, v74, v74 row_half_mirror row_mask:0xf bank_mask:0xf bound_ctrl:1
	v_add_f32_dpp v36, v75, v75 row_half_mirror row_mask:0xf bank_mask:0xf bound_ctrl:1
	s_nop 0
	v_mov_b32_dpp v77, v76 row_ror:8 row_mask:0xf bank_mask:0xf bound_ctrl:1
	s_waitcnt lgkmcnt(7)
	v_pk_mul_f32 v[66:67], v[76:77], v[28:29] op_sel_hi:[1,0]
	v_pk_mul_f32 v[68:69], v[76:77], v[28:29] op_sel:[0,1]
	v_pk_mul_f32 v[70:71], v[76:77], v[30:31] op_sel_hi:[1,0]
	v_pk_mul_f32 v[72:73], v[76:77], v[30:31] op_sel:[0,1]
	v_pk_fma_f32 v[66:67], v[32:33], v[24:25], v[66:67] op_sel_hi:[1,0,1]
	v_pk_fma_f32 v[68:69], v[32:33], v[24:25], v[68:69] op_sel:[0,1,0]
	v_pk_fma_f32 v[70:71], v[32:33], v[26:27], v[70:71] op_sel_hi:[1,0,1]
	v_pk_fma_f32 v[72:73], v[32:33], v[26:27], v[72:73] op_sel:[0,1,0]
	v_pk_fma_f32 v[0:1], v[0:1], v[20:21], v[66:67] op_sel_hi:[1,0,1]
	v_pk_fma_f32 v[2:3], v[2:3], v[20:21], v[68:69] op_sel:[0,1,0]
	v_pk_fma_f32 v[4:5], v[4:5], v[22:23], v[70:71] op_sel_hi:[1,0,1]
	v_pk_fma_f32 v[6:7], v[6:7], v[22:23], v[72:73] op_sel:[0,1,0]
	ds_write_b32 v84, v36 offset:0
	ds_write_b32 v84, v76 offset:12288
	s_waitcnt lgkmcnt(7)
	v_pk_mul_f32 v[8:9], v[0:1], v[40:41] op_sel_hi:[1,0]
	v_pk_mul_f32 v[10:11], v[0:1], v[44:45] op_sel_hi:[1,0]
	ds_read_b128 v[12:15], v80 offset:3840
	v_pk_fma_f32 v[8:9], v[2:3], v[40:41], v[8:9] op_sel:[0,1,0]
	v_pk_fma_f32 v[10:11], v[2:3], v[44:45], v[10:11] op_sel:[0,1,0]
	ds_read_b128 v[16:19], v80 offset:3072
	v_pk_fma_f32 v[8:9], v[4:5], v[42:43], v[8:9] op_sel_hi:[1,0,1]
	v_pk_fma_f32 v[10:11], v[4:5], v[46:47], v[10:11] op_sel_hi:[1,0,1]
	ds_read_b128 v[20:23], v80 offset:3328
	v_pk_fma_f32 v[8:9], v[6:7], v[42:43], v[8:9] op_sel:[0,1,0]
	v_pk_fma_f32 v[10:11], v[6:7], v[46:47], v[10:11] op_sel:[0,1,0]
	ds_read_b128 v[24:27], v80 offset:3584
	v_add_f32_dpp v74, v9, v8 row_ror:8 row_mask:0xf bank_mask:0xf bound_ctrl:1
	v_add_f32_dpp v75, v11, v10 row_ror:8 row_mask:0xf bank_mask:0xf bound_ctrl:1
	ds_read_b128 v[28:31], v80 offset:4096
	v_add_f32_dpp v74, v74, v74 quad_perm:[1,0,3,2] row_mask:0xf bank_mask:0xf bound_ctrl:1
	v_add_f32_dpp v75, v75, v75 quad_perm:[1,0,3,2] row_mask:0xf bank_mask:0xf bound_ctrl:1
	ds_read_b32 v32, v81 offset:4352
	v_add_f32_dpp v74, v74, v74 quad_perm:[2,3,0,1] row_mask:0xf bank_mask:0xf bound_ctrl:1
	v_add_f32_dpp v75, v75, v75 quad_perm:[2,3,0,1] row_mask:0xf bank_mask:0xf bound_ctrl:1
	ds_read_b32 v33, v82 offset:4352
	v_add_f32_dpp v76, v74, v74 row_half_mirror row_mask:0xf bank_mask:0xf bound_ctrl:1
	v_add_f32_dpp v64, v75, v75 row_half_mirror row_mask:0xf bank_mask:0xf bound_ctrl:1
	s_nop 0
	v_mov_b32_dpp v77, v76 row_ror:8 row_mask:0xf bank_mask:0xf bound_ctrl:1
	s_waitcnt lgkmcnt(9)
	v_pk_mul_f32 v[66:67], v[76:77], v[56:57] op_sel_hi:[1,0]
	v_pk_mul_f32 v[68:69], v[76:77], v[56:57] op_sel:[0,1]
	v_pk_mul_f32 v[70:71], v[76:77], v[58:59] op_sel_hi:[1,0]
	v_pk_mul_f32 v[72:73], v[76:77], v[58:59] op_sel:[0,1]
	v_pk_fma_f32 v[66:67], v[60:61], v[52:53], v[66:67] op_sel_hi:[1,0,1]
	v_pk_fma_f32 v[68:69], v[60:61], v[52:53], v[68:69] op_sel:[0,1,0]
	v_pk_fma_f32 v[70:71], v[60:61], v[54:55], v[70:71] op_sel_hi:[1,0,1]
	v_pk_fma_f32 v[72:73], v[60:61], v[54:55], v[72:73] op_sel:[0,1,0]
	v_pk_fma_f32 v[0:1], v[0:1], v[48:49], v[66:67] op_sel_hi:[1,0,1]
	v_pk_fma_f32 v[2:3], v[2:3], v[48:49], v[68:69] op_sel:[0,1,0]
	v_pk_fma_f32 v[4:5], v[4:5], v[50:51], v[70:71] op_sel_hi:[1,0,1]
	v_pk_fma_f32 v[6:7], v[6:7], v[50:51], v[72:73] op_sel:[0,1,0]
	ds_write_b32 v84, v64 offset:128
	ds_write_b32 v84, v76 offset:12416
	s_waitcnt lgkmcnt(7)
	v_pk_mul_f32 v[8:9], v[0:1], v[12:13] op_sel_hi:[1,0]
	v_pk_mul_f32 v[10:11], v[0:1], v[16:17] op_sel_hi:[1,0]
	ds_read_b128 v[40:43], v80 offset:5376
	v_pk_fma_f32 v[8:9], v[2:3], v[12:13], v[8:9] op_sel:[0,1,0]
	v_pk_fma_f32 v[10:11], v[2:3], v[16:17], v[10:11] op_sel:[0,1,0]
	ds_read_b128 v[44:47], v80 offset:4608
	v_pk_fma_f32 v[8:9], v[4:5], v[14:15], v[8:9] op_sel_hi:[1,0,1]
	v_pk_fma_f32 v[10:11], v[4:5], v[18:19], v[10:11] op_sel_hi:[1,0,1]
	ds_read_b128 v[48:51], v80 offset:4864
	v_pk_fma_f32 v[8:9], v[6:7], v[14:15], v[8:9] op_sel:[0,1,0]
	v_pk_fma_f32 v[10:11], v[6:7], v[18:19], v[10:11] op_sel:[0,1,0]
	ds_read_b128 v[52:55], v80 offset:5120
	v_add_f32_dpp v74, v9, v8 row_ror:8 row_mask:0xf bank_mask:0xf bound_ctrl:1
	v_add_f32_dpp v75, v11, v10 row_ror:8 row_mask:0xf bank_mask:0xf bound_ctrl:1
	ds_read_b128 v[56:59], v80 offset:5632
	v_add_f32_dpp v74, v74, v74 quad_perm:[1,0,3,2] row_mask:0xf bank_mask:0xf bound_ctrl:1
	v_add_f32_dpp v75, v75, v75 quad_perm:[1,0,3,2] row_mask:0xf bank_mask:0xf bound_ctrl:1
	ds_read_b32 v60, v81 offset:5888
	v_add_f32_dpp v74, v74, v74 quad_perm:[2,3,0,1] row_mask:0xf bank_mask:0xf bound_ctrl:1
	v_add_f32_dpp v75, v75, v75 quad_perm:[2,3,0,1] row_mask:0xf bank_mask:0xf bound_ctrl:1
	ds_read_b32 v61, v82 offset:5888
	v_add_f32_dpp v76, v74, v74 row_half_mirror row_mask:0xf bank_mask:0xf bound_ctrl:1
	v_add_f32_dpp v36, v75, v75 row_half_mirror row_mask:0xf bank_mask:0xf bound_ctrl:1
	s_nop 0
	v_mov_b32_dpp v77, v76 row_ror:8 row_mask:0xf bank_mask:0xf bound_ctrl:1
	s_waitcnt lgkmcnt(9)
	v_pk_mul_f32 v[66:67], v[76:77], v[28:29] op_sel_hi:[1,0]
	v_pk_mul_f32 v[68:69], v[76:77], v[28:29] op_sel:[0,1]
	v_pk_mul_f32 v[70:71], v[76:77], v[30:31] op_sel_hi:[1,0]
	v_pk_mul_f32 v[72:73], v[76:77], v[30:31] op_sel:[0,1]
	v_pk_fma_f32 v[66:67], v[32:33], v[24:25], v[66:67] op_sel_hi:[1,0,1]
	v_pk_fma_f32 v[68:69], v[32:33], v[24:25], v[68:69] op_sel:[0,1,0]
	v_pk_fma_f32 v[70:71], v[32:33], v[26:27], v[70:71] op_sel_hi:[1,0,1]
	v_pk_fma_f32 v[72:73], v[32:33], v[26:27], v[72:73] op_sel:[0,1,0]
	v_pk_fma_f32 v[0:1], v[0:1], v[20:21], v[66:67] op_sel_hi:[1,0,1]
	v_pk_fma_f32 v[2:3], v[2:3], v[20:21], v[68:69] op_sel:[0,1,0]
	v_pk_fma_f32 v[4:5], v[4:5], v[22:23], v[70:71] op_sel_hi:[1,0,1]
	v_pk_fma_f32 v[6:7], v[6:7], v[22:23], v[72:73] op_sel:[0,1,0]
	ds_write_b32 v84, v36 offset:256
	ds_write_b32 v84, v76 offset:12544
	s_waitcnt lgkmcnt(7)
	v_pk_mul_f32 v[8:9], v[0:1], v[40:41] op_sel_hi:[1,0]
	v_pk_mul_f32 v[10:11], v[0:1], v[44:45] op_sel_hi:[1,0]
	ds_read_b128 v[12:15], v80 offset:6912
	v_pk_fma_f32 v[8:9], v[2:3], v[40:41], v[8:9] op_sel:[0,1,0]
	v_pk_fma_f32 v[10:11], v[2:3], v[44:45], v[10:11] op_sel:[0,1,0]
	ds_read_b128 v[16:19], v80 offset:6144
	v_pk_fma_f32 v[8:9], v[4:5], v[42:43], v[8:9] op_sel_hi:[1,0,1]
	v_pk_fma_f32 v[10:11], v[4:5], v[46:47], v[10:11] op_sel_hi:[1,0,1]
	ds_read_b128 v[20:23], v80 offset:6400
	v_pk_fma_f32 v[8:9], v[6:7], v[42:43], v[8:9] op_sel:[0,1,0]
	v_pk_fma_f32 v[10:11], v[6:7], v[46:47], v[10:11] op_sel:[0,1,0]
	ds_read_b128 v[24:27], v80 offset:6656
	v_add_f32_dpp v74, v9, v8 row_ror:8 row_mask:0xf bank_mask:0xf bound_ctrl:1
	v_add_f32_dpp v75, v11, v10 row_ror:8 row_mask:0xf bank_mask:0xf bound_ctrl:1
	ds_read_b128 v[28:31], v80 offset:7168
	v_add_f32_dpp v74, v74, v74 quad_perm:[1,0,3,2] row_mask:0xf bank_mask:0xf bound_ctrl:1
	v_add_f32_dpp v75, v75, v75 quad_perm:[1,0,3,2] row_mask:0xf bank_mask:0xf bound_ctrl:1
	ds_read_b32 v32, v81 offset:7424
	v_add_f32_dpp v74, v74, v74 quad_perm:[2,3,0,1] row_mask:0xf bank_mask:0xf bound_ctrl:1
	v_add_f32_dpp v75, v75, v75 quad_perm:[2,3,0,1] row_mask:0xf bank_mask:0xf bound_ctrl:1
	ds_read_b32 v33, v82 offset:7424
	v_add_f32_dpp v76, v74, v74 row_half_mirror row_mask:0xf bank_mask:0xf bound_ctrl:1
	v_add_f32_dpp v64, v75, v75 row_half_mirror row_mask:0xf bank_mask:0xf bound_ctrl:1
	s_nop 0
	v_mov_b32_dpp v77, v76 row_ror:8 row_mask:0xf bank_mask:0xf bound_ctrl:1
	s_waitcnt lgkmcnt(9)
	v_pk_mul_f32 v[66:67], v[76:77], v[56:57] op_sel_hi:[1,0]
	v_pk_mul_f32 v[68:69], v[76:77], v[56:57] op_sel:[0,1]
	v_pk_mul_f32 v[70:71], v[76:77], v[58:59] op_sel_hi:[1,0]
	v_pk_mul_f32 v[72:73], v[76:77], v[58:59] op_sel:[0,1]
	v_pk_fma_f32 v[66:67], v[60:61], v[52:53], v[66:67] op_sel_hi:[1,0,1]
	v_pk_fma_f32 v[68:69], v[60:61], v[52:53], v[68:69] op_sel:[0,1,0]
	v_pk_fma_f32 v[70:71], v[60:61], v[54:55], v[70:71] op_sel_hi:[1,0,1]
	v_pk_fma_f32 v[72:73], v[60:61], v[54:55], v[72:73] op_sel:[0,1,0]
	v_pk_fma_f32 v[0:1], v[0:1], v[48:49], v[66:67] op_sel_hi:[1,0,1]
	v_pk_fma_f32 v[2:3], v[2:3], v[48:49], v[68:69] op_sel:[0,1,0]
	v_pk_fma_f32 v[4:5], v[4:5], v[50:51], v[70:71] op_sel_hi:[1,0,1]
	v_pk_fma_f32 v[6:7], v[6:7], v[50:51], v[72:73] op_sel:[0,1,0]
	ds_write_b32 v84, v64 offset:384
	ds_write_b32 v84, v76 offset:12672
	s_waitcnt lgkmcnt(7)
	v_pk_mul_f32 v[8:9], v[0:1], v[12:13] op_sel_hi:[1,0]
	v_pk_mul_f32 v[10:11], v[0:1], v[16:17] op_sel_hi:[1,0]
	ds_read_b128 v[40:43], v80 offset:8448
	v_pk_fma_f32 v[8:9], v[2:3], v[12:13], v[8:9] op_sel:[0,1,0]
	v_pk_fma_f32 v[10:11], v[2:3], v[16:17], v[10:11] op_sel:[0,1,0]
	ds_read_b128 v[44:47], v80 offset:7680
	v_pk_fma_f32 v[8:9], v[4:5], v[14:15], v[8:9] op_sel_hi:[1,0,1]
	v_pk_fma_f32 v[10:11], v[4:5], v[18:19], v[10:11] op_sel_hi:[1,0,1]
	ds_read_b128 v[48:51], v80 offset:7936
	v_pk_fma_f32 v[8:9], v[6:7], v[14:15], v[8:9] op_sel:[0,1,0]
	v_pk_fma_f32 v[10:11], v[6:7], v[18:19], v[10:11] op_sel:[0,1,0]
	ds_read_b128 v[52:55], v80 offset:8192
	v_add_f32_dpp v74, v9, v8 row_ror:8 row_mask:0xf bank_mask:0xf bound_ctrl:1
	v_add_f32_dpp v75, v11, v10 row_ror:8 row_mask:0xf bank_mask:0xf bound_ctrl:1
	ds_read_b128 v[56:59], v80 offset:8704
	v_add_f32_dpp v74, v74, v74 quad_perm:[1,0,3,2] row_mask:0xf bank_mask:0xf bound_ctrl:1
	v_add_f32_dpp v75, v75, v75 quad_perm:[1,0,3,2] row_mask:0xf bank_mask:0xf bound_ctrl:1
	ds_read_b32 v60, v81 offset:8960
	v_add_f32_dpp v74, v74, v74 quad_perm:[2,3,0,1] row_mask:0xf bank_mask:0xf bound_ctrl:1
	v_add_f32_dpp v75, v75, v75 quad_perm:[2,3,0,1] row_mask:0xf bank_mask:0xf bound_ctrl:1
	ds_read_b32 v61, v82 offset:8960
	v_add_f32_dpp v76, v74, v74 row_half_mirror row_mask:0xf bank_mask:0xf bound_ctrl:1
	v_add_f32_dpp v36, v75, v75 row_half_mirror row_mask:0xf bank_mask:0xf bound_ctrl:1
	s_nop 0
	v_mov_b32_dpp v77, v76 row_ror:8 row_mask:0xf bank_mask:0xf bound_ctrl:1
	s_waitcnt lgkmcnt(9)
	v_pk_mul_f32 v[66:67], v[76:77], v[28:29] op_sel_hi:[1,0]
	v_pk_mul_f32 v[68:69], v[76:77], v[28:29] op_sel:[0,1]
	v_pk_mul_f32 v[70:71], v[76:77], v[30:31] op_sel_hi:[1,0]
	v_pk_mul_f32 v[72:73], v[76:77], v[30:31] op_sel:[0,1]
	v_pk_fma_f32 v[66:67], v[32:33], v[24:25], v[66:67] op_sel_hi:[1,0,1]
	v_pk_fma_f32 v[68:69], v[32:33], v[24:25], v[68:69] op_sel:[0,1,0]
	v_pk_fma_f32 v[70:71], v[32:33], v[26:27], v[70:71] op_sel_hi:[1,0,1]
	v_pk_fma_f32 v[72:73], v[32:33], v[26:27], v[72:73] op_sel:[0,1,0]
	v_pk_fma_f32 v[0:1], v[0:1], v[20:21], v[66:67] op_sel_hi:[1,0,1]
	v_pk_fma_f32 v[2:3], v[2:3], v[20:21], v[68:69] op_sel:[0,1,0]
	v_pk_fma_f32 v[4:5], v[4:5], v[22:23], v[70:71] op_sel_hi:[1,0,1]
	v_pk_fma_f32 v[6:7], v[6:7], v[22:23], v[72:73] op_sel:[0,1,0]
	ds_write_b32 v84, v36 offset:512
	ds_write_b32 v84, v76 offset:12800
	s_waitcnt lgkmcnt(7)
	v_pk_mul_f32 v[8:9], v[0:1], v[40:41] op_sel_hi:[1,0]
	v_pk_mul_f32 v[10:11], v[0:1], v[44:45] op_sel_hi:[1,0]
	ds_read_b128 v[12:15], v80 offset:9984
	v_pk_fma_f32 v[8:9], v[2:3], v[40:41], v[8:9] op_sel:[0,1,0]
	v_pk_fma_f32 v[10:11], v[2:3], v[44:45], v[10:11] op_sel:[0,1,0]
	ds_read_b128 v[16:19], v80 offset:9216
	v_pk_fma_f32 v[8:9], v[4:5], v[42:43], v[8:9] op_sel_hi:[1,0,1]
	v_pk_fma_f32 v[10:11], v[4:5], v[46:47], v[10:11] op_sel_hi:[1,0,1]
	ds_read_b128 v[20:23], v80 offset:9472
	v_pk_fma_f32 v[8:9], v[6:7], v[42:43], v[8:9] op_sel:[0,1,0]
	v_pk_fma_f32 v[10:11], v[6:7], v[46:47], v[10:11] op_sel:[0,1,0]
	ds_read_b128 v[24:27], v80 offset:9728
	v_add_f32_dpp v74, v9, v8 row_ror:8 row_mask:0xf bank_mask:0xf bound_ctrl:1
	v_add_f32_dpp v75, v11, v10 row_ror:8 row_mask:0xf bank_mask:0xf bound_ctrl:1
	ds_read_b128 v[28:31], v80 offset:10240
	v_add_f32_dpp v74, v74, v74 quad_perm:[1,0,3,2] row_mask:0xf bank_mask:0xf bound_ctrl:1
	v_add_f32_dpp v75, v75, v75 quad_perm:[1,0,3,2] row_mask:0xf bank_mask:0xf bound_ctrl:1
	ds_read_b32 v32, v81 offset:10496
	v_add_f32_dpp v74, v74, v74 quad_perm:[2,3,0,1] row_mask:0xf bank_mask:0xf bound_ctrl:1
	v_add_f32_dpp v75, v75, v75 quad_perm:[2,3,0,1] row_mask:0xf bank_mask:0xf bound_ctrl:1
	ds_read_b32 v33, v82 offset:10496
	v_add_f32_dpp v76, v74, v74 row_half_mirror row_mask:0xf bank_mask:0xf bound_ctrl:1
	v_add_f32_dpp v64, v75, v75 row_half_mirror row_mask:0xf bank_mask:0xf bound_ctrl:1
	s_nop 0
	v_mov_b32_dpp v77, v76 row_ror:8 row_mask:0xf bank_mask:0xf bound_ctrl:1
	s_waitcnt lgkmcnt(9)
	v_pk_mul_f32 v[66:67], v[76:77], v[56:57] op_sel_hi:[1,0]
	v_pk_mul_f32 v[68:69], v[76:77], v[56:57] op_sel:[0,1]
	v_pk_mul_f32 v[70:71], v[76:77], v[58:59] op_sel_hi:[1,0]
	v_pk_mul_f32 v[72:73], v[76:77], v[58:59] op_sel:[0,1]
	v_pk_fma_f32 v[66:67], v[60:61], v[52:53], v[66:67] op_sel_hi:[1,0,1]
	v_pk_fma_f32 v[68:69], v[60:61], v[52:53], v[68:69] op_sel:[0,1,0]
	v_pk_fma_f32 v[70:71], v[60:61], v[54:55], v[70:71] op_sel_hi:[1,0,1]
	v_pk_fma_f32 v[72:73], v[60:61], v[54:55], v[72:73] op_sel:[0,1,0]
	v_pk_fma_f32 v[0:1], v[0:1], v[48:49], v[66:67] op_sel_hi:[1,0,1]
	v_pk_fma_f32 v[2:3], v[2:3], v[48:49], v[68:69] op_sel:[0,1,0]
	v_pk_fma_f32 v[4:5], v[4:5], v[50:51], v[70:71] op_sel_hi:[1,0,1]
	v_pk_fma_f32 v[6:7], v[6:7], v[50:51], v[72:73] op_sel:[0,1,0]
	ds_write_b32 v84, v64 offset:640
	ds_write_b32 v84, v76 offset:12928
	s_waitcnt lgkmcnt(7)
	v_pk_mul_f32 v[8:9], v[0:1], v[12:13] op_sel_hi:[1,0]
	v_pk_mul_f32 v[10:11], v[0:1], v[16:17] op_sel_hi:[1,0]
	ds_read_b128 v[40:43], v80 offset:11520
	v_pk_fma_f32 v[8:9], v[2:3], v[12:13], v[8:9] op_sel:[0,1,0]
	v_pk_fma_f32 v[10:11], v[2:3], v[16:17], v[10:11] op_sel:[0,1,0]
	ds_read_b128 v[44:47], v80 offset:10752
	v_pk_fma_f32 v[8:9], v[4:5], v[14:15], v[8:9] op_sel_hi:[1,0,1]
	v_pk_fma_f32 v[10:11], v[4:5], v[18:19], v[10:11] op_sel_hi:[1,0,1]
	ds_read_b128 v[48:51], v80 offset:11008
	v_pk_fma_f32 v[8:9], v[6:7], v[14:15], v[8:9] op_sel:[0,1,0]
	v_pk_fma_f32 v[10:11], v[6:7], v[18:19], v[10:11] op_sel:[0,1,0]
	ds_read_b128 v[52:55], v80 offset:11264
	v_add_f32_dpp v74, v9, v8 row_ror:8 row_mask:0xf bank_mask:0xf bound_ctrl:1
	v_add_f32_dpp v75, v11, v10 row_ror:8 row_mask:0xf bank_mask:0xf bound_ctrl:1
	ds_read_b128 v[56:59], v80 offset:11776
	v_add_f32_dpp v74, v74, v74 quad_perm:[1,0,3,2] row_mask:0xf bank_mask:0xf bound_ctrl:1
	v_add_f32_dpp v75, v75, v75 quad_perm:[1,0,3,2] row_mask:0xf bank_mask:0xf bound_ctrl:1
	ds_read_b32 v60, v81 offset:12032
	v_add_f32_dpp v74, v74, v74 quad_perm:[2,3,0,1] row_mask:0xf bank_mask:0xf bound_ctrl:1
	v_add_f32_dpp v75, v75, v75 quad_perm:[2,3,0,1] row_mask:0xf bank_mask:0xf bound_ctrl:1
	ds_read_b32 v61, v82 offset:12032
	v_add_f32_dpp v76, v74, v74 row_half_mirror row_mask:0xf bank_mask:0xf bound_ctrl:1
	v_add_f32_dpp v36, v75, v75 row_half_mirror row_mask:0xf bank_mask:0xf bound_ctrl:1
	s_nop 0
	v_mov_b32_dpp v77, v76 row_ror:8 row_mask:0xf bank_mask:0xf bound_ctrl:1
	s_waitcnt lgkmcnt(9)
	v_pk_mul_f32 v[66:67], v[76:77], v[28:29] op_sel_hi:[1,0]
	v_pk_mul_f32 v[68:69], v[76:77], v[28:29] op_sel:[0,1]
	v_pk_mul_f32 v[70:71], v[76:77], v[30:31] op_sel_hi:[1,0]
	v_pk_mul_f32 v[72:73], v[76:77], v[30:31] op_sel:[0,1]
	v_pk_fma_f32 v[66:67], v[32:33], v[24:25], v[66:67] op_sel_hi:[1,0,1]
	v_pk_fma_f32 v[68:69], v[32:33], v[24:25], v[68:69] op_sel:[0,1,0]
	v_pk_fma_f32 v[70:71], v[32:33], v[26:27], v[70:71] op_sel_hi:[1,0,1]
	v_pk_fma_f32 v[72:73], v[32:33], v[26:27], v[72:73] op_sel:[0,1,0]
	v_pk_fma_f32 v[0:1], v[0:1], v[20:21], v[66:67] op_sel_hi:[1,0,1]
	v_pk_fma_f32 v[2:3], v[2:3], v[20:21], v[68:69] op_sel:[0,1,0]
	v_pk_fma_f32 v[4:5], v[4:5], v[22:23], v[70:71] op_sel_hi:[1,0,1]
	v_pk_fma_f32 v[6:7], v[6:7], v[22:23], v[72:73] op_sel:[0,1,0]
	ds_write_b32 v84, v36 offset:768
	ds_write_b32 v84, v76 offset:13056
	s_waitcnt lgkmcnt(7)
	v_pk_mul_f32 v[8:9], v[0:1], v[40:41] op_sel_hi:[1,0]
	v_pk_mul_f32 v[10:11], v[0:1], v[44:45] op_sel_hi:[1,0]
	ds_read_b128 v[12:15], v80 offset:13056
	v_pk_fma_f32 v[8:9], v[2:3], v[40:41], v[8:9] op_sel:[0,1,0]
	v_pk_fma_f32 v[10:11], v[2:3], v[44:45], v[10:11] op_sel:[0,1,0]
	ds_read_b128 v[16:19], v80 offset:12288
	v_pk_fma_f32 v[8:9], v[4:5], v[42:43], v[8:9] op_sel_hi:[1,0,1]
	v_pk_fma_f32 v[10:11], v[4:5], v[46:47], v[10:11] op_sel_hi:[1,0,1]
	ds_read_b128 v[20:23], v80 offset:12544
	v_pk_fma_f32 v[8:9], v[6:7], v[42:43], v[8:9] op_sel:[0,1,0]
	v_pk_fma_f32 v[10:11], v[6:7], v[46:47], v[10:11] op_sel:[0,1,0]
	ds_read_b128 v[24:27], v80 offset:12800
	v_add_f32_dpp v74, v9, v8 row_ror:8 row_mask:0xf bank_mask:0xf bound_ctrl:1
	v_add_f32_dpp v75, v11, v10 row_ror:8 row_mask:0xf bank_mask:0xf bound_ctrl:1
	ds_read_b128 v[28:31], v80 offset:13312
	v_add_f32_dpp v74, v74, v74 quad_perm:[1,0,3,2] row_mask:0xf bank_mask:0xf bound_ctrl:1
	v_add_f32_dpp v75, v75, v75 quad_perm:[1,0,3,2] row_mask:0xf bank_mask:0xf bound_ctrl:1
	ds_read_b32 v32, v81 offset:13568
	v_add_f32_dpp v74, v74, v74 quad_perm:[2,3,0,1] row_mask:0xf bank_mask:0xf bound_ctrl:1
	v_add_f32_dpp v75, v75, v75 quad_perm:[2,3,0,1] row_mask:0xf bank_mask:0xf bound_ctrl:1
	ds_read_b32 v33, v82 offset:13568
	v_add_f32_dpp v76, v74, v74 row_half_mirror row_mask:0xf bank_mask:0xf bound_ctrl:1
	v_add_f32_dpp v64, v75, v75 row_half_mirror row_mask:0xf bank_mask:0xf bound_ctrl:1
	s_nop 0
	v_mov_b32_dpp v77, v76 row_ror:8 row_mask:0xf bank_mask:0xf bound_ctrl:1
	s_waitcnt lgkmcnt(9)
	v_pk_mul_f32 v[66:67], v[76:77], v[56:57] op_sel_hi:[1,0]
	v_pk_mul_f32 v[68:69], v[76:77], v[56:57] op_sel:[0,1]
	v_pk_mul_f32 v[70:71], v[76:77], v[58:59] op_sel_hi:[1,0]
	v_pk_mul_f32 v[72:73], v[76:77], v[58:59] op_sel:[0,1]
	v_pk_fma_f32 v[66:67], v[60:61], v[52:53], v[66:67] op_sel_hi:[1,0,1]
	v_pk_fma_f32 v[68:69], v[60:61], v[52:53], v[68:69] op_sel:[0,1,0]
	v_pk_fma_f32 v[70:71], v[60:61], v[54:55], v[70:71] op_sel_hi:[1,0,1]
	v_pk_fma_f32 v[72:73], v[60:61], v[54:55], v[72:73] op_sel:[0,1,0]
	v_pk_fma_f32 v[0:1], v[0:1], v[48:49], v[66:67] op_sel_hi:[1,0,1]
	v_pk_fma_f32 v[2:3], v[2:3], v[48:49], v[68:69] op_sel:[0,1,0]
	v_pk_fma_f32 v[4:5], v[4:5], v[50:51], v[70:71] op_sel_hi:[1,0,1]
	v_pk_fma_f32 v[6:7], v[6:7], v[50:51], v[72:73] op_sel:[0,1,0]
	ds_write_b32 v84, v64 offset:896
	ds_write_b32 v84, v76 offset:13184
	s_waitcnt lgkmcnt(7)
	v_pk_mul_f32 v[8:9], v[0:1], v[12:13] op_sel_hi:[1,0]
	v_pk_mul_f32 v[10:11], v[0:1], v[16:17] op_sel_hi:[1,0]
	ds_read_b128 v[40:43], v80 offset:14592
	v_pk_fma_f32 v[8:9], v[2:3], v[12:13], v[8:9] op_sel:[0,1,0]
	v_pk_fma_f32 v[10:11], v[2:3], v[16:17], v[10:11] op_sel:[0,1,0]
	ds_read_b128 v[44:47], v80 offset:13824
	v_pk_fma_f32 v[8:9], v[4:5], v[14:15], v[8:9] op_sel_hi:[1,0,1]
	v_pk_fma_f32 v[10:11], v[4:5], v[18:19], v[10:11] op_sel_hi:[1,0,1]
	ds_read_b128 v[48:51], v80 offset:14080
	v_pk_fma_f32 v[8:9], v[6:7], v[14:15], v[8:9] op_sel:[0,1,0]
	v_pk_fma_f32 v[10:11], v[6:7], v[18:19], v[10:11] op_sel:[0,1,0]
	ds_read_b128 v[52:55], v80 offset:14336
	v_add_f32_dpp v74, v9, v8 row_ror:8 row_mask:0xf bank_mask:0xf bound_ctrl:1
	v_add_f32_dpp v75, v11, v10 row_ror:8 row_mask:0xf bank_mask:0xf bound_ctrl:1
	ds_read_b128 v[56:59], v80 offset:14848
	v_add_f32_dpp v74, v74, v74 quad_perm:[1,0,3,2] row_mask:0xf bank_mask:0xf bound_ctrl:1
	v_add_f32_dpp v75, v75, v75 quad_perm:[1,0,3,2] row_mask:0xf bank_mask:0xf bound_ctrl:1
	ds_read_b32 v60, v81 offset:15104
	v_add_f32_dpp v74, v74, v74 quad_perm:[2,3,0,1] row_mask:0xf bank_mask:0xf bound_ctrl:1
	v_add_f32_dpp v75, v75, v75 quad_perm:[2,3,0,1] row_mask:0xf bank_mask:0xf bound_ctrl:1
	ds_read_b32 v61, v82 offset:15104
	v_add_f32_dpp v76, v74, v74 row_half_mirror row_mask:0xf bank_mask:0xf bound_ctrl:1
	v_add_f32_dpp v36, v75, v75 row_half_mirror row_mask:0xf bank_mask:0xf bound_ctrl:1
	s_nop 0
	v_mov_b32_dpp v77, v76 row_ror:8 row_mask:0xf bank_mask:0xf bound_ctrl:1
	s_waitcnt lgkmcnt(9)
	v_pk_mul_f32 v[66:67], v[76:77], v[28:29] op_sel_hi:[1,0]
	v_pk_mul_f32 v[68:69], v[76:77], v[28:29] op_sel:[0,1]
	v_pk_mul_f32 v[70:71], v[76:77], v[30:31] op_sel_hi:[1,0]
	v_pk_mul_f32 v[72:73], v[76:77], v[30:31] op_sel:[0,1]
	v_pk_fma_f32 v[66:67], v[32:33], v[24:25], v[66:67] op_sel_hi:[1,0,1]
	v_pk_fma_f32 v[68:69], v[32:33], v[24:25], v[68:69] op_sel:[0,1,0]
	v_pk_fma_f32 v[70:71], v[32:33], v[26:27], v[70:71] op_sel_hi:[1,0,1]
	v_pk_fma_f32 v[72:73], v[32:33], v[26:27], v[72:73] op_sel:[0,1,0]
	v_pk_fma_f32 v[0:1], v[0:1], v[20:21], v[66:67] op_sel_hi:[1,0,1]
	v_pk_fma_f32 v[2:3], v[2:3], v[20:21], v[68:69] op_sel:[0,1,0]
	v_pk_fma_f32 v[4:5], v[4:5], v[22:23], v[70:71] op_sel_hi:[1,0,1]
	v_pk_fma_f32 v[6:7], v[6:7], v[22:23], v[72:73] op_sel:[0,1,0]
	ds_write_b32 v84, v36 offset:1024
	ds_write_b32 v84, v76 offset:13312
	s_waitcnt lgkmcnt(7)
	v_pk_mul_f32 v[8:9], v[0:1], v[40:41] op_sel_hi:[1,0]
	v_pk_mul_f32 v[10:11], v[0:1], v[44:45] op_sel_hi:[1,0]
	ds_read_b128 v[12:15], v80 offset:16128
	v_pk_fma_f32 v[8:9], v[2:3], v[40:41], v[8:9] op_sel:[0,1,0]
	v_pk_fma_f32 v[10:11], v[2:3], v[44:45], v[10:11] op_sel:[0,1,0]
	ds_read_b128 v[16:19], v80 offset:15360
	v_pk_fma_f32 v[8:9], v[4:5], v[42:43], v[8:9] op_sel_hi:[1,0,1]
	v_pk_fma_f32 v[10:11], v[4:5], v[46:47], v[10:11] op_sel_hi:[1,0,1]
	ds_read_b128 v[20:23], v80 offset:15616
	v_pk_fma_f32 v[8:9], v[6:7], v[42:43], v[8:9] op_sel:[0,1,0]
	v_pk_fma_f32 v[10:11], v[6:7], v[46:47], v[10:11] op_sel:[0,1,0]
	ds_read_b128 v[24:27], v80 offset:15872
	v_add_f32_dpp v74, v9, v8 row_ror:8 row_mask:0xf bank_mask:0xf bound_ctrl:1
	v_add_f32_dpp v75, v11, v10 row_ror:8 row_mask:0xf bank_mask:0xf bound_ctrl:1
	ds_read_b128 v[28:31], v80 offset:16384
	v_add_f32_dpp v74, v74, v74 quad_perm:[1,0,3,2] row_mask:0xf bank_mask:0xf bound_ctrl:1
	v_add_f32_dpp v75, v75, v75 quad_perm:[1,0,3,2] row_mask:0xf bank_mask:0xf bound_ctrl:1
	ds_read_b32 v32, v81 offset:16640
	v_add_f32_dpp v74, v74, v74 quad_perm:[2,3,0,1] row_mask:0xf bank_mask:0xf bound_ctrl:1
	v_add_f32_dpp v75, v75, v75 quad_perm:[2,3,0,1] row_mask:0xf bank_mask:0xf bound_ctrl:1
	ds_read_b32 v33, v82 offset:16640
	v_add_f32_dpp v76, v74, v74 row_half_mirror row_mask:0xf bank_mask:0xf bound_ctrl:1
	v_add_f32_dpp v64, v75, v75 row_half_mirror row_mask:0xf bank_mask:0xf bound_ctrl:1
	s_nop 0
	v_mov_b32_dpp v77, v76 row_ror:8 row_mask:0xf bank_mask:0xf bound_ctrl:1
	s_waitcnt lgkmcnt(9)
	v_pk_mul_f32 v[66:67], v[76:77], v[56:57] op_sel_hi:[1,0]
	v_pk_mul_f32 v[68:69], v[76:77], v[56:57] op_sel:[0,1]
	v_pk_mul_f32 v[70:71], v[76:77], v[58:59] op_sel_hi:[1,0]
	v_pk_mul_f32 v[72:73], v[76:77], v[58:59] op_sel:[0,1]
	v_pk_fma_f32 v[66:67], v[60:61], v[52:53], v[66:67] op_sel_hi:[1,0,1]
	v_pk_fma_f32 v[68:69], v[60:61], v[52:53], v[68:69] op_sel:[0,1,0]
	v_pk_fma_f32 v[70:71], v[60:61], v[54:55], v[70:71] op_sel_hi:[1,0,1]
	v_pk_fma_f32 v[72:73], v[60:61], v[54:55], v[72:73] op_sel:[0,1,0]
	v_pk_fma_f32 v[0:1], v[0:1], v[48:49], v[66:67] op_sel_hi:[1,0,1]
	v_pk_fma_f32 v[2:3], v[2:3], v[48:49], v[68:69] op_sel:[0,1,0]
	v_pk_fma_f32 v[4:5], v[4:5], v[50:51], v[70:71] op_sel_hi:[1,0,1]
	v_pk_fma_f32 v[6:7], v[6:7], v[50:51], v[72:73] op_sel:[0,1,0]
	ds_write_b32 v84, v64 offset:1152
	ds_write_b32 v84, v76 offset:13440
	s_waitcnt lgkmcnt(7)
	v_pk_mul_f32 v[8:9], v[0:1], v[12:13] op_sel_hi:[1,0]
	v_pk_mul_f32 v[10:11], v[0:1], v[16:17] op_sel_hi:[1,0]
	ds_read_b128 v[40:43], v80 offset:17664
	v_pk_fma_f32 v[8:9], v[2:3], v[12:13], v[8:9] op_sel:[0,1,0]
	v_pk_fma_f32 v[10:11], v[2:3], v[16:17], v[10:11] op_sel:[0,1,0]
	ds_read_b128 v[44:47], v80 offset:16896
	v_pk_fma_f32 v[8:9], v[4:5], v[14:15], v[8:9] op_sel_hi:[1,0,1]
	v_pk_fma_f32 v[10:11], v[4:5], v[18:19], v[10:11] op_sel_hi:[1,0,1]
	ds_read_b128 v[48:51], v80 offset:17152
	v_pk_fma_f32 v[8:9], v[6:7], v[14:15], v[8:9] op_sel:[0,1,0]
	v_pk_fma_f32 v[10:11], v[6:7], v[18:19], v[10:11] op_sel:[0,1,0]
	ds_read_b128 v[52:55], v80 offset:17408
	v_add_f32_dpp v74, v9, v8 row_ror:8 row_mask:0xf bank_mask:0xf bound_ctrl:1
	v_add_f32_dpp v75, v11, v10 row_ror:8 row_mask:0xf bank_mask:0xf bound_ctrl:1
	ds_read_b128 v[56:59], v80 offset:17920
	v_add_f32_dpp v74, v74, v74 quad_perm:[1,0,3,2] row_mask:0xf bank_mask:0xf bound_ctrl:1
	v_add_f32_dpp v75, v75, v75 quad_perm:[1,0,3,2] row_mask:0xf bank_mask:0xf bound_ctrl:1
	ds_read_b32 v60, v81 offset:18176
	v_add_f32_dpp v74, v74, v74 quad_perm:[2,3,0,1] row_mask:0xf bank_mask:0xf bound_ctrl:1
	v_add_f32_dpp v75, v75, v75 quad_perm:[2,3,0,1] row_mask:0xf bank_mask:0xf bound_ctrl:1
	ds_read_b32 v61, v82 offset:18176
	v_add_f32_dpp v76, v74, v74 row_half_mirror row_mask:0xf bank_mask:0xf bound_ctrl:1
	v_add_f32_dpp v36, v75, v75 row_half_mirror row_mask:0xf bank_mask:0xf bound_ctrl:1
	s_nop 0
	v_mov_b32_dpp v77, v76 row_ror:8 row_mask:0xf bank_mask:0xf bound_ctrl:1
	s_waitcnt lgkmcnt(9)
	v_pk_mul_f32 v[66:67], v[76:77], v[28:29] op_sel_hi:[1,0]
	v_pk_mul_f32 v[68:69], v[76:77], v[28:29] op_sel:[0,1]
	v_pk_mul_f32 v[70:71], v[76:77], v[30:31] op_sel_hi:[1,0]
	v_pk_mul_f32 v[72:73], v[76:77], v[30:31] op_sel:[0,1]
	v_pk_fma_f32 v[66:67], v[32:33], v[24:25], v[66:67] op_sel_hi:[1,0,1]
	v_pk_fma_f32 v[68:69], v[32:33], v[24:25], v[68:69] op_sel:[0,1,0]
	v_pk_fma_f32 v[70:71], v[32:33], v[26:27], v[70:71] op_sel_hi:[1,0,1]
	v_pk_fma_f32 v[72:73], v[32:33], v[26:27], v[72:73] op_sel:[0,1,0]
	v_pk_fma_f32 v[0:1], v[0:1], v[20:21], v[66:67] op_sel_hi:[1,0,1]
	v_pk_fma_f32 v[2:3], v[2:3], v[20:21], v[68:69] op_sel:[0,1,0]
	v_pk_fma_f32 v[4:5], v[4:5], v[22:23], v[70:71] op_sel_hi:[1,0,1]
	v_pk_fma_f32 v[6:7], v[6:7], v[22:23], v[72:73] op_sel:[0,1,0]
	ds_write_b32 v84, v36 offset:1280
	ds_write_b32 v84, v76 offset:13568
	s_waitcnt lgkmcnt(7)
	v_pk_mul_f32 v[8:9], v[0:1], v[40:41] op_sel_hi:[1,0]
	v_pk_mul_f32 v[10:11], v[0:1], v[44:45] op_sel_hi:[1,0]
	ds_read_b128 v[12:15], v80 offset:19200
	v_pk_fma_f32 v[8:9], v[2:3], v[40:41], v[8:9] op_sel:[0,1,0]
	v_pk_fma_f32 v[10:11], v[2:3], v[44:45], v[10:11] op_sel:[0,1,0]
	ds_read_b128 v[16:19], v80 offset:18432
	v_pk_fma_f32 v[8:9], v[4:5], v[42:43], v[8:9] op_sel_hi:[1,0,1]
	v_pk_fma_f32 v[10:11], v[4:5], v[46:47], v[10:11] op_sel_hi:[1,0,1]
	ds_read_b128 v[20:23], v80 offset:18688
	v_pk_fma_f32 v[8:9], v[6:7], v[42:43], v[8:9] op_sel:[0,1,0]
	v_pk_fma_f32 v[10:11], v[6:7], v[46:47], v[10:11] op_sel:[0,1,0]
	ds_read_b128 v[24:27], v80 offset:18944
	v_add_f32_dpp v74, v9, v8 row_ror:8 row_mask:0xf bank_mask:0xf bound_ctrl:1
	v_add_f32_dpp v75, v11, v10 row_ror:8 row_mask:0xf bank_mask:0xf bound_ctrl:1
	ds_read_b128 v[28:31], v80 offset:19456
	v_add_f32_dpp v74, v74, v74 quad_perm:[1,0,3,2] row_mask:0xf bank_mask:0xf bound_ctrl:1
	v_add_f32_dpp v75, v75, v75 quad_perm:[1,0,3,2] row_mask:0xf bank_mask:0xf bound_ctrl:1
	ds_read_b32 v32, v81 offset:19712
	v_add_f32_dpp v74, v74, v74 quad_perm:[2,3,0,1] row_mask:0xf bank_mask:0xf bound_ctrl:1
	v_add_f32_dpp v75, v75, v75 quad_perm:[2,3,0,1] row_mask:0xf bank_mask:0xf bound_ctrl:1
	ds_read_b32 v33, v82 offset:19712
	v_add_f32_dpp v76, v74, v74 row_half_mirror row_mask:0xf bank_mask:0xf bound_ctrl:1
	v_add_f32_dpp v64, v75, v75 row_half_mirror row_mask:0xf bank_mask:0xf bound_ctrl:1
	s_nop 0
	v_mov_b32_dpp v77, v76 row_ror:8 row_mask:0xf bank_mask:0xf bound_ctrl:1
	s_waitcnt lgkmcnt(9)
	v_pk_mul_f32 v[66:67], v[76:77], v[56:57] op_sel_hi:[1,0]
	v_pk_mul_f32 v[68:69], v[76:77], v[56:57] op_sel:[0,1]
	v_pk_mul_f32 v[70:71], v[76:77], v[58:59] op_sel_hi:[1,0]
	v_pk_mul_f32 v[72:73], v[76:77], v[58:59] op_sel:[0,1]
	v_pk_fma_f32 v[66:67], v[60:61], v[52:53], v[66:67] op_sel_hi:[1,0,1]
	v_pk_fma_f32 v[68:69], v[60:61], v[52:53], v[68:69] op_sel:[0,1,0]
	v_pk_fma_f32 v[70:71], v[60:61], v[54:55], v[70:71] op_sel_hi:[1,0,1]
	v_pk_fma_f32 v[72:73], v[60:61], v[54:55], v[72:73] op_sel:[0,1,0]
	v_pk_fma_f32 v[0:1], v[0:1], v[48:49], v[66:67] op_sel_hi:[1,0,1]
	v_pk_fma_f32 v[2:3], v[2:3], v[48:49], v[68:69] op_sel:[0,1,0]
	v_pk_fma_f32 v[4:5], v[4:5], v[50:51], v[70:71] op_sel_hi:[1,0,1]
	v_pk_fma_f32 v[6:7], v[6:7], v[50:51], v[72:73] op_sel:[0,1,0]
	ds_write_b32 v84, v64 offset:1408
	ds_write_b32 v84, v76 offset:13696
	s_waitcnt lgkmcnt(7)
	v_pk_mul_f32 v[8:9], v[0:1], v[12:13] op_sel_hi:[1,0]
	v_pk_mul_f32 v[10:11], v[0:1], v[16:17] op_sel_hi:[1,0]
	ds_read_b128 v[40:43], v80 offset:20736
	v_pk_fma_f32 v[8:9], v[2:3], v[12:13], v[8:9] op_sel:[0,1,0]
	v_pk_fma_f32 v[10:11], v[2:3], v[16:17], v[10:11] op_sel:[0,1,0]
	ds_read_b128 v[44:47], v80 offset:19968
	v_pk_fma_f32 v[8:9], v[4:5], v[14:15], v[8:9] op_sel_hi:[1,0,1]
	v_pk_fma_f32 v[10:11], v[4:5], v[18:19], v[10:11] op_sel_hi:[1,0,1]
	ds_read_b128 v[48:51], v80 offset:20224
	v_pk_fma_f32 v[8:9], v[6:7], v[14:15], v[8:9] op_sel:[0,1,0]
	v_pk_fma_f32 v[10:11], v[6:7], v[18:19], v[10:11] op_sel:[0,1,0]
	ds_read_b128 v[52:55], v80 offset:20480
	v_add_f32_dpp v74, v9, v8 row_ror:8 row_mask:0xf bank_mask:0xf bound_ctrl:1
	v_add_f32_dpp v75, v11, v10 row_ror:8 row_mask:0xf bank_mask:0xf bound_ctrl:1
	ds_read_b128 v[56:59], v80 offset:20992
	v_add_f32_dpp v74, v74, v74 quad_perm:[1,0,3,2] row_mask:0xf bank_mask:0xf bound_ctrl:1
	v_add_f32_dpp v75, v75, v75 quad_perm:[1,0,3,2] row_mask:0xf bank_mask:0xf bound_ctrl:1
	ds_read_b32 v60, v81 offset:21248
	v_add_f32_dpp v74, v74, v74 quad_perm:[2,3,0,1] row_mask:0xf bank_mask:0xf bound_ctrl:1
	v_add_f32_dpp v75, v75, v75 quad_perm:[2,3,0,1] row_mask:0xf bank_mask:0xf bound_ctrl:1
	ds_read_b32 v61, v82 offset:21248
	v_add_f32_dpp v76, v74, v74 row_half_mirror row_mask:0xf bank_mask:0xf bound_ctrl:1
	v_add_f32_dpp v36, v75, v75 row_half_mirror row_mask:0xf bank_mask:0xf bound_ctrl:1
	s_nop 0
	v_mov_b32_dpp v77, v76 row_ror:8 row_mask:0xf bank_mask:0xf bound_ctrl:1
	s_waitcnt lgkmcnt(9)
	v_pk_mul_f32 v[66:67], v[76:77], v[28:29] op_sel_hi:[1,0]
	v_pk_mul_f32 v[68:69], v[76:77], v[28:29] op_sel:[0,1]
	v_pk_mul_f32 v[70:71], v[76:77], v[30:31] op_sel_hi:[1,0]
	v_pk_mul_f32 v[72:73], v[76:77], v[30:31] op_sel:[0,1]
	v_pk_fma_f32 v[66:67], v[32:33], v[24:25], v[66:67] op_sel_hi:[1,0,1]
	v_pk_fma_f32 v[68:69], v[32:33], v[24:25], v[68:69] op_sel:[0,1,0]
	v_pk_fma_f32 v[70:71], v[32:33], v[26:27], v[70:71] op_sel_hi:[1,0,1]
	v_pk_fma_f32 v[72:73], v[32:33], v[26:27], v[72:73] op_sel:[0,1,0]
	v_pk_fma_f32 v[0:1], v[0:1], v[20:21], v[66:67] op_sel_hi:[1,0,1]
	v_pk_fma_f32 v[2:3], v[2:3], v[20:21], v[68:69] op_sel:[0,1,0]
	v_pk_fma_f32 v[4:5], v[4:5], v[22:23], v[70:71] op_sel_hi:[1,0,1]
	v_pk_fma_f32 v[6:7], v[6:7], v[22:23], v[72:73] op_sel:[0,1,0]
	ds_write_b32 v84, v36 offset:1536
	ds_write_b32 v84, v76 offset:13824
	s_waitcnt lgkmcnt(7)
	v_pk_mul_f32 v[8:9], v[0:1], v[40:41] op_sel_hi:[1,0]
	v_pk_mul_f32 v[10:11], v[0:1], v[44:45] op_sel_hi:[1,0]
	ds_read_b128 v[12:15], v80 offset:22272
	v_pk_fma_f32 v[8:9], v[2:3], v[40:41], v[8:9] op_sel:[0,1,0]
	v_pk_fma_f32 v[10:11], v[2:3], v[44:45], v[10:11] op_sel:[0,1,0]
	ds_read_b128 v[16:19], v80 offset:21504
	v_pk_fma_f32 v[8:9], v[4:5], v[42:43], v[8:9] op_sel_hi:[1,0,1]
	v_pk_fma_f32 v[10:11], v[4:5], v[46:47], v[10:11] op_sel_hi:[1,0,1]
	ds_read_b128 v[20:23], v80 offset:21760
	v_pk_fma_f32 v[8:9], v[6:7], v[42:43], v[8:9] op_sel:[0,1,0]
	v_pk_fma_f32 v[10:11], v[6:7], v[46:47], v[10:11] op_sel:[0,1,0]
	ds_read_b128 v[24:27], v80 offset:22016
	v_add_f32_dpp v74, v9, v8 row_ror:8 row_mask:0xf bank_mask:0xf bound_ctrl:1
	v_add_f32_dpp v75, v11, v10 row_ror:8 row_mask:0xf bank_mask:0xf bound_ctrl:1
	ds_read_b128 v[28:31], v80 offset:22528
	v_add_f32_dpp v74, v74, v74 quad_perm:[1,0,3,2] row_mask:0xf bank_mask:0xf bound_ctrl:1
	v_add_f32_dpp v75, v75, v75 quad_perm:[1,0,3,2] row_mask:0xf bank_mask:0xf bound_ctrl:1
	ds_read_b32 v32, v81 offset:22784
	v_add_f32_dpp v74, v74, v74 quad_perm:[2,3,0,1] row_mask:0xf bank_mask:0xf bound_ctrl:1
	v_add_f32_dpp v75, v75, v75 quad_perm:[2,3,0,1] row_mask:0xf bank_mask:0xf bound_ctrl:1
	ds_read_b32 v33, v82 offset:22784
	v_add_f32_dpp v76, v74, v74 row_half_mirror row_mask:0xf bank_mask:0xf bound_ctrl:1
	v_add_f32_dpp v64, v75, v75 row_half_mirror row_mask:0xf bank_mask:0xf bound_ctrl:1
	s_nop 0
	v_mov_b32_dpp v77, v76 row_ror:8 row_mask:0xf bank_mask:0xf bound_ctrl:1
	s_waitcnt lgkmcnt(9)
	v_pk_mul_f32 v[66:67], v[76:77], v[56:57] op_sel_hi:[1,0]
	v_pk_mul_f32 v[68:69], v[76:77], v[56:57] op_sel:[0,1]
	v_pk_mul_f32 v[70:71], v[76:77], v[58:59] op_sel_hi:[1,0]
	v_pk_mul_f32 v[72:73], v[76:77], v[58:59] op_sel:[0,1]
	v_pk_fma_f32 v[66:67], v[60:61], v[52:53], v[66:67] op_sel_hi:[1,0,1]
	v_pk_fma_f32 v[68:69], v[60:61], v[52:53], v[68:69] op_sel:[0,1,0]
	v_pk_fma_f32 v[70:71], v[60:61], v[54:55], v[70:71] op_sel_hi:[1,0,1]
	v_pk_fma_f32 v[72:73], v[60:61], v[54:55], v[72:73] op_sel:[0,1,0]
	v_pk_fma_f32 v[0:1], v[0:1], v[48:49], v[66:67] op_sel_hi:[1,0,1]
	v_pk_fma_f32 v[2:3], v[2:3], v[48:49], v[68:69] op_sel:[0,1,0]
	v_pk_fma_f32 v[4:5], v[4:5], v[50:51], v[70:71] op_sel_hi:[1,0,1]
	v_pk_fma_f32 v[6:7], v[6:7], v[50:51], v[72:73] op_sel:[0,1,0]
	ds_write_b32 v84, v64 offset:1664
	ds_write_b32 v84, v76 offset:13952
	s_waitcnt lgkmcnt(7)
	v_pk_mul_f32 v[8:9], v[0:1], v[12:13] op_sel_hi:[1,0]
	v_pk_mul_f32 v[10:11], v[0:1], v[16:17] op_sel_hi:[1,0]
	ds_read_b128 v[40:43], v80 offset:23808
	v_pk_fma_f32 v[8:9], v[2:3], v[12:13], v[8:9] op_sel:[0,1,0]
	v_pk_fma_f32 v[10:11], v[2:3], v[16:17], v[10:11] op_sel:[0,1,0]
	ds_read_b128 v[44:47], v80 offset:23040
	v_pk_fma_f32 v[8:9], v[4:5], v[14:15], v[8:9] op_sel_hi:[1,0,1]
	v_pk_fma_f32 v[10:11], v[4:5], v[18:19], v[10:11] op_sel_hi:[1,0,1]
	ds_read_b128 v[48:51], v80 offset:23296
	v_pk_fma_f32 v[8:9], v[6:7], v[14:15], v[8:9] op_sel:[0,1,0]
	v_pk_fma_f32 v[10:11], v[6:7], v[18:19], v[10:11] op_sel:[0,1,0]
	ds_read_b128 v[52:55], v80 offset:23552
	v_add_f32_dpp v74, v9, v8 row_ror:8 row_mask:0xf bank_mask:0xf bound_ctrl:1
	v_add_f32_dpp v75, v11, v10 row_ror:8 row_mask:0xf bank_mask:0xf bound_ctrl:1
	ds_read_b128 v[56:59], v80 offset:24064
	v_add_f32_dpp v74, v74, v74 quad_perm:[1,0,3,2] row_mask:0xf bank_mask:0xf bound_ctrl:1
	v_add_f32_dpp v75, v75, v75 quad_perm:[1,0,3,2] row_mask:0xf bank_mask:0xf bound_ctrl:1
	ds_read_b32 v60, v81 offset:24320
	v_add_f32_dpp v74, v74, v74 quad_perm:[2,3,0,1] row_mask:0xf bank_mask:0xf bound_ctrl:1
	v_add_f32_dpp v75, v75, v75 quad_perm:[2,3,0,1] row_mask:0xf bank_mask:0xf bound_ctrl:1
	ds_read_b32 v61, v82 offset:24320
	v_add_f32_dpp v76, v74, v74 row_half_mirror row_mask:0xf bank_mask:0xf bound_ctrl:1
	v_add_f32_dpp v36, v75, v75 row_half_mirror row_mask:0xf bank_mask:0xf bound_ctrl:1
	s_nop 0
	v_mov_b32_dpp v77, v76 row_ror:8 row_mask:0xf bank_mask:0xf bound_ctrl:1
	s_waitcnt lgkmcnt(9)
	v_pk_mul_f32 v[66:67], v[76:77], v[28:29] op_sel_hi:[1,0]
	v_pk_mul_f32 v[68:69], v[76:77], v[28:29] op_sel:[0,1]
	v_pk_mul_f32 v[70:71], v[76:77], v[30:31] op_sel_hi:[1,0]
	v_pk_mul_f32 v[72:73], v[76:77], v[30:31] op_sel:[0,1]
	v_pk_fma_f32 v[66:67], v[32:33], v[24:25], v[66:67] op_sel_hi:[1,0,1]
	v_pk_fma_f32 v[68:69], v[32:33], v[24:25], v[68:69] op_sel:[0,1,0]
	v_pk_fma_f32 v[70:71], v[32:33], v[26:27], v[70:71] op_sel_hi:[1,0,1]
	v_pk_fma_f32 v[72:73], v[32:33], v[26:27], v[72:73] op_sel:[0,1,0]
	v_pk_fma_f32 v[0:1], v[0:1], v[20:21], v[66:67] op_sel_hi:[1,0,1]
	v_pk_fma_f32 v[2:3], v[2:3], v[20:21], v[68:69] op_sel:[0,1,0]
	v_pk_fma_f32 v[4:5], v[4:5], v[22:23], v[70:71] op_sel_hi:[1,0,1]
	v_pk_fma_f32 v[6:7], v[6:7], v[22:23], v[72:73] op_sel:[0,1,0]
	ds_write_b32 v84, v36 offset:1792
	ds_write_b32 v84, v76 offset:14080
	s_waitcnt lgkmcnt(7)
	v_pk_mul_f32 v[8:9], v[0:1], v[40:41] op_sel_hi:[1,0]
	v_pk_mul_f32 v[10:11], v[0:1], v[44:45] op_sel_hi:[1,0]
	ds_read_b128 v[12:15], v80 offset:25344
	v_pk_fma_f32 v[8:9], v[2:3], v[40:41], v[8:9] op_sel:[0,1,0]
	v_pk_fma_f32 v[10:11], v[2:3], v[44:45], v[10:11] op_sel:[0,1,0]
	ds_read_b128 v[16:19], v80 offset:24576
	v_pk_fma_f32 v[8:9], v[4:5], v[42:43], v[8:9] op_sel_hi:[1,0,1]
	v_pk_fma_f32 v[10:11], v[4:5], v[46:47], v[10:11] op_sel_hi:[1,0,1]
	ds_read_b128 v[20:23], v80 offset:24832
	v_pk_fma_f32 v[8:9], v[6:7], v[42:43], v[8:9] op_sel:[0,1,0]
	v_pk_fma_f32 v[10:11], v[6:7], v[46:47], v[10:11] op_sel:[0,1,0]
	ds_read_b128 v[24:27], v80 offset:25088
	v_add_f32_dpp v74, v9, v8 row_ror:8 row_mask:0xf bank_mask:0xf bound_ctrl:1
	v_add_f32_dpp v75, v11, v10 row_ror:8 row_mask:0xf bank_mask:0xf bound_ctrl:1
	ds_read_b128 v[28:31], v80 offset:25600
	v_add_f32_dpp v74, v74, v74 quad_perm:[1,0,3,2] row_mask:0xf bank_mask:0xf bound_ctrl:1
	v_add_f32_dpp v75, v75, v75 quad_perm:[1,0,3,2] row_mask:0xf bank_mask:0xf bound_ctrl:1
	ds_read_b32 v32, v81 offset:25856
	v_add_f32_dpp v74, v74, v74 quad_perm:[2,3,0,1] row_mask:0xf bank_mask:0xf bound_ctrl:1
	v_add_f32_dpp v75, v75, v75 quad_perm:[2,3,0,1] row_mask:0xf bank_mask:0xf bound_ctrl:1
	ds_read_b32 v33, v82 offset:25856
	v_add_f32_dpp v76, v74, v74 row_half_mirror row_mask:0xf bank_mask:0xf bound_ctrl:1
	v_add_f32_dpp v64, v75, v75 row_half_mirror row_mask:0xf bank_mask:0xf bound_ctrl:1
	s_nop 0
	v_mov_b32_dpp v77, v76 row_ror:8 row_mask:0xf bank_mask:0xf bound_ctrl:1
	s_waitcnt lgkmcnt(9)
	v_pk_mul_f32 v[66:67], v[76:77], v[56:57] op_sel_hi:[1,0]
	v_pk_mul_f32 v[68:69], v[76:77], v[56:57] op_sel:[0,1]
	v_pk_mul_f32 v[70:71], v[76:77], v[58:59] op_sel_hi:[1,0]
	v_pk_mul_f32 v[72:73], v[76:77], v[58:59] op_sel:[0,1]
	v_pk_fma_f32 v[66:67], v[60:61], v[52:53], v[66:67] op_sel_hi:[1,0,1]
	v_pk_fma_f32 v[68:69], v[60:61], v[52:53], v[68:69] op_sel:[0,1,0]
	v_pk_fma_f32 v[70:71], v[60:61], v[54:55], v[70:71] op_sel_hi:[1,0,1]
	v_pk_fma_f32 v[72:73], v[60:61], v[54:55], v[72:73] op_sel:[0,1,0]
	v_pk_fma_f32 v[0:1], v[0:1], v[48:49], v[66:67] op_sel_hi:[1,0,1]
	v_pk_fma_f32 v[2:3], v[2:3], v[48:49], v[68:69] op_sel:[0,1,0]
	v_pk_fma_f32 v[4:5], v[4:5], v[50:51], v[70:71] op_sel_hi:[1,0,1]
	v_pk_fma_f32 v[6:7], v[6:7], v[50:51], v[72:73] op_sel:[0,1,0]
	ds_write_b32 v84, v64 offset:1920
	ds_write_b32 v84, v76 offset:14208
	s_cmp_eq_u32 s4, 64
	s_cbranch_scc1 .Lrec_chunk_end
	s_waitcnt lgkmcnt(7)
	v_pk_mul_f32 v[8:9], v[0:1], v[12:13] op_sel_hi:[1,0]
	v_pk_mul_f32 v[10:11], v[0:1], v[16:17] op_sel_hi:[1,0]
	ds_read_b128 v[40:43], v80 offset:26880
	v_pk_fma_f32 v[8:9], v[2:3], v[12:13], v[8:9] op_sel:[0,1,0]
	v_pk_fma_f32 v[10:11], v[2:3], v[16:17], v[10:11] op_sel:[0,1,0]
	ds_read_b128 v[44:47], v80 offset:26112
	v_pk_fma_f32 v[8:9], v[4:5], v[14:15], v[8:9] op_sel_hi:[1,0,1]
	v_pk_fma_f32 v[10:11], v[4:5], v[18:19], v[10:11] op_sel_hi:[1,0,1]
	ds_read_b128 v[48:51], v80 offset:26368
	v_pk_fma_f32 v[8:9], v[6:7], v[14:15], v[8:9] op_sel:[0,1,0]
	v_pk_fma_f32 v[10:11], v[6:7], v[18:19], v[10:11] op_sel:[0,1,0]
	ds_read_b128 v[52:55], v80 offset:26624
	v_add_f32_dpp v74, v9, v8 row_ror:8 row_mask:0xf bank_mask:0xf bound_ctrl:1
	v_add_f32_dpp v75, v11, v10 row_ror:8 row_mask:0xf bank_mask:0xf bound_ctrl:1
	ds_read_b128 v[56:59], v80 offset:27136
	v_add_f32_dpp v74, v74, v74 quad_perm:[1,0,3,2] row_mask:0xf bank_mask:0xf bound_ctrl:1
	v_add_f32_dpp v75, v75, v75 quad_perm:[1,0,3,2] row_mask:0xf bank_mask:0xf bound_ctrl:1
	ds_read_b32 v60, v81 offset:27392
	v_add_f32_dpp v74, v74, v74 quad_perm:[2,3,0,1] row_mask:0xf bank_mask:0xf bound_ctrl:1
	v_add_f32_dpp v75, v75, v75 quad_perm:[2,3,0,1] row_mask:0xf bank_mask:0xf bound_ctrl:1
	ds_read_b32 v61, v82 offset:27392
	v_add_f32_dpp v76, v74, v74 row_half_mirror row_mask:0xf bank_mask:0xf bound_ctrl:1
	v_add_f32_dpp v36, v75, v75 row_half_mirror row_mask:0xf bank_mask:0xf bound_ctrl:1
	s_nop 0
	v_mov_b32_dpp v77, v76 row_ror:8 row_mask:0xf bank_mask:0xf bound_ctrl:1
	s_waitcnt lgkmcnt(9)
	v_pk_mul_f32 v[66:67], v[76:77], v[28:29] op_sel_hi:[1,0]
	v_pk_mul_f32 v[68:69], v[76:77], v[28:29] op_sel:[0,1]
	v_pk_mul_f32 v[70:71], v[76:77], v[30:31] op_sel_hi:[1,0]
	v_pk_mul_f32 v[72:73], v[76:77], v[30:31] op_sel:[0,1]
	v_pk_fma_f32 v[66:67], v[32:33], v[24:25], v[66:67] op_sel_hi:[1,0,1]
	v_pk_fma_f32 v[68:69], v[32:33], v[24:25], v[68:69] op_sel:[0,1,0]
	v_pk_fma_f32 v[70:71], v[32:33], v[26:27], v[70:71] op_sel_hi:[1,0,1]
	v_pk_fma_f32 v[72:73], v[32:33], v[26:27], v[72:73] op_sel:[0,1,0]
	v_pk_fma_f32 v[0:1], v[0:1], v[20:21], v[66:67] op_sel_hi:[1,0,1]
	v_pk_fma_f32 v[2:3], v[2:3], v[20:21], v[68:69] op_sel:[0,1,0]
	v_pk_fma_f32 v[4:5], v[4:5], v[22:23], v[70:71] op_sel_hi:[1,0,1]
	v_pk_fma_f32 v[6:7], v[6:7], v[22:23], v[72:73] op_sel:[0,1,0]
	ds_write_b32 v84, v36 offset:2048
	ds_write_b32 v84, v76 offset:14336
	s_waitcnt lgkmcnt(7)
	v_pk_mul_f32 v[8:9], v[0:1], v[40:41] op_sel_hi:[1,0]
	v_pk_mul_f32 v[10:11], v[0:1], v[44:45] op_sel_hi:[1,0]
	ds_read_b128 v[12:15], v80 offset:28416
	v_pk_fma_f32 v[8:9], v[2:3], v[40:41], v[8:9] op_sel:[0,1,0]
	v_pk_fma_f32 v[10:11], v[2:3], v[44:45], v[10:11] op_sel:[0,1,0]
	ds_read_b128 v[16:19], v80 offset:27648
	v_pk_fma_f32 v[8:9], v[4:5], v[42:43], v[8:9] op_sel_hi:[1,0,1]
	v_pk_fma_f32 v[10:11], v[4:5], v[46:47], v[10:11] op_sel_hi:[1,0,1]
	ds_read_b128 v[20:23], v80 offset:27904
	v_pk_fma_f32 v[8:9], v[6:7], v[42:43], v[8:9] op_sel:[0,1,0]
	v_pk_fma_f32 v[10:11], v[6:7], v[46:47], v[10:11] op_sel:[0,1,0]
	ds_read_b128 v[24:27], v80 offset:28160
	v_add_f32_dpp v74, v9, v8 row_ror:8 row_mask:0xf bank_mask:0xf bound_ctrl:1
	v_add_f32_dpp v75, v11, v10 row_ror:8 row_mask:0xf bank_mask:0xf bound_ctrl:1
	ds_read_b128 v[28:31], v80 offset:28672
	v_add_f32_dpp v74, v74, v74 quad_perm:[1,0,3,2] row_mask:0xf bank_mask:0xf bound_ctrl:1
	v_add_f32_dpp v75, v75, v75 quad_perm:[1,0,3,2] row_mask:0xf bank_mask:0xf bound_ctrl:1
	ds_read_b32 v32, v81 offset:28928
	v_add_f32_dpp v74, v74, v74 quad_perm:[2,3,0,1] row_mask:0xf bank_mask:0xf bound_ctrl:1
	v_add_f32_dpp v75, v75, v75 quad_perm:[2,3,0,1] row_mask:0xf bank_mask:0xf bound_ctrl:1
	ds_read_b32 v33, v82 offset:28928
	v_add_f32_dpp v76, v74, v74 row_half_mirror row_mask:0xf bank_mask:0xf bound_ctrl:1
	v_add_f32_dpp v64, v75, v75 row_half_mirror row_mask:0xf bank_mask:0xf bound_ctrl:1
	s_nop 0
	v_mov_b32_dpp v77, v76 row_ror:8 row_mask:0xf bank_mask:0xf bound_ctrl:1
	s_waitcnt lgkmcnt(9)
	v_pk_mul_f32 v[66:67], v[76:77], v[56:57] op_sel_hi:[1,0]
	v_pk_mul_f32 v[68:69], v[76:77], v[56:57] op_sel:[0,1]
	v_pk_mul_f32 v[70:71], v[76:77], v[58:59] op_sel_hi:[1,0]
	v_pk_mul_f32 v[72:73], v[76:77], v[58:59] op_sel:[0,1]
	v_pk_fma_f32 v[66:67], v[60:61], v[52:53], v[66:67] op_sel_hi:[1,0,1]
	v_pk_fma_f32 v[68:69], v[60:61], v[52:53], v[68:69] op_sel:[0,1,0]
	v_pk_fma_f32 v[70:71], v[60:61], v[54:55], v[70:71] op_sel_hi:[1,0,1]
	v_pk_fma_f32 v[72:73], v[60:61], v[54:55], v[72:73] op_sel:[0,1,0]
	v_pk_fma_f32 v[0:1], v[0:1], v[48:49], v[66:67] op_sel_hi:[1,0,1]
	v_pk_fma_f32 v[2:3], v[2:3], v[48:49], v[68:69] op_sel:[0,1,0]
	v_pk_fma_f32 v[4:5], v[4:5], v[50:51], v[70:71] op_sel_hi:[1,0,1]
	v_pk_fma_f32 v[6:7], v[6:7], v[50:51], v[72:73] op_sel:[0,1,0]
	ds_write_b32 v84, v64 offset:2176
	ds_write_b32 v84, v76 offset:14464
	s_waitcnt lgkmcnt(7)
	v_pk_mul_f32 v[8:9], v[0:1], v[12:13] op_sel_hi:[1,0]
	v_pk_mul_f32 v[10:11], v[0:1], v[16:17] op_sel_hi:[1,0]
	ds_read_b128 v[40:43], v80 offset:29952
	v_pk_fma_f32 v[8:9], v[2:3], v[12:13], v[8:9] op_sel:[0,1,0]
	v_pk_fma_f32 v[10:11], v[2:3], v[16:17], v[10:11] op_sel:[0,1,0]
	ds_read_b128 v[44:47], v80 offset:29184
	v_pk_fma_f32 v[8:9], v[4:5], v[14:15], v[8:9] op_sel_hi:[1,0,1]
	v_pk_fma_f32 v[10:11], v[4:5], v[18:19], v[10:11] op_sel_hi:[1,0,1]
	ds_read_b128 v[48:51], v80 offset:29440
	v_pk_fma_f32 v[8:9], v[6:7], v[14:15], v[8:9] op_sel:[0,1,0]
	v_pk_fma_f32 v[10:11], v[6:7], v[18:19], v[10:11] op_sel:[0,1,0]
	ds_read_b128 v[52:55], v80 offset:29696
	v_add_f32_dpp v74, v9, v8 row_ror:8 row_mask:0xf bank_mask:0xf bound_ctrl:1
	v_add_f32_dpp v75, v11, v10 row_ror:8 row_mask:0xf bank_mask:0xf bound_ctrl:1
	ds_read_b128 v[56:59], v80 offset:30208
	v_add_f32_dpp v74, v74, v74 quad_perm:[1,0,3,2] row_mask:0xf bank_mask:0xf bound_ctrl:1
	v_add_f32_dpp v75, v75, v75 quad_perm:[1,0,3,2] row_mask:0xf bank_mask:0xf bound_ctrl:1
	ds_read_b32 v60, v81 offset:30464
	v_add_f32_dpp v74, v74, v74 quad_perm:[2,3,0,1] row_mask:0xf bank_mask:0xf bound_ctrl:1
	v_add_f32_dpp v75, v75, v75 quad_perm:[2,3,0,1] row_mask:0xf bank_mask:0xf bound_ctrl:1
	ds_read_b32 v61, v82 offset:30464
	v_add_f32_dpp v76, v74, v74 row_half_mirror row_mask:0xf bank_mask:0xf bound_ctrl:1
	v_add_f32_dpp v36, v75, v75 row_half_mirror row_mask:0xf bank_mask:0xf bound_ctrl:1
	s_nop 0
	v_mov_b32_dpp v77, v76 row_ror:8 row_mask:0xf bank_mask:0xf bound_ctrl:1
	s_waitcnt lgkmcnt(9)
	v_pk_mul_f32 v[66:67], v[76:77], v[28:29] op_sel_hi:[1,0]
	v_pk_mul_f32 v[68:69], v[76:77], v[28:29] op_sel:[0,1]
	v_pk_mul_f32 v[70:71], v[76:77], v[30:31] op_sel_hi:[1,0]
	v_pk_mul_f32 v[72:73], v[76:77], v[30:31] op_sel:[0,1]
	v_pk_fma_f32 v[66:67], v[32:33], v[24:25], v[66:67] op_sel_hi:[1,0,1]
	v_pk_fma_f32 v[68:69], v[32:33], v[24:25], v[68:69] op_sel:[0,1,0]
	v_pk_fma_f32 v[70:71], v[32:33], v[26:27], v[70:71] op_sel_hi:[1,0,1]
	v_pk_fma_f32 v[72:73], v[32:33], v[26:27], v[72:73] op_sel:[0,1,0]
	v_pk_fma_f32 v[0:1], v[0:1], v[20:21], v[66:67] op_sel_hi:[1,0,1]
	v_pk_fma_f32 v[2:3], v[2:3], v[20:21], v[68:69] op_sel:[0,1,0]
	v_pk_fma_f32 v[4:5], v[4:5], v[22:23], v[70:71] op_sel_hi:[1,0,1]
	v_pk_fma_f32 v[6:7], v[6:7], v[22:23], v[72:73] op_sel:[0,1,0]
	ds_write_b32 v84, v36 offset:2304
	ds_write_b32 v84, v76 offset:14592
	s_waitcnt lgkmcnt(7)
	v_pk_mul_f32 v[8:9], v[0:1], v[40:41] op_sel_hi:[1,0]
	v_pk_mul_f32 v[10:11], v[0:1], v[44:45] op_sel_hi:[1,0]
	ds_read_b128 v[12:15], v80 offset:31488
	v_pk_fma_f32 v[8:9], v[2:3], v[40:41], v[8:9] op_sel:[0,1,0]
	v_pk_fma_f32 v[10:11], v[2:3], v[44:45], v[10:11] op_sel:[0,1,0]
	ds_read_b128 v[16:19], v80 offset:30720
	v_pk_fma_f32 v[8:9], v[4:5], v[42:43], v[8:9] op_sel_hi:[1,0,1]
	v_pk_fma_f32 v[10:11], v[4:5], v[46:47], v[10:11] op_sel_hi:[1,0,1]
	ds_read_b128 v[20:23], v80 offset:30976
	v_pk_fma_f32 v[8:9], v[6:7], v[42:43], v[8:9] op_sel:[0,1,0]
	v_pk_fma_f32 v[10:11], v[6:7], v[46:47], v[10:11] op_sel:[0,1,0]
	ds_read_b128 v[24:27], v80 offset:31232
	v_add_f32_dpp v74, v9, v8 row_ror:8 row_mask:0xf bank_mask:0xf bound_ctrl:1
	v_add_f32_dpp v75, v11, v10 row_ror:8 row_mask:0xf bank_mask:0xf bound_ctrl:1
	ds_read_b128 v[28:31], v80 offset:31744
	v_add_f32_dpp v74, v74, v74 quad_perm:[1,0,3,2] row_mask:0xf bank_mask:0xf bound_ctrl:1
	v_add_f32_dpp v75, v75, v75 quad_perm:[1,0,3,2] row_mask:0xf bank_mask:0xf bound_ctrl:1
	ds_read_b32 v32, v81 offset:32000
	v_add_f32_dpp v74, v74, v74 quad_perm:[2,3,0,1] row_mask:0xf bank_mask:0xf bound_ctrl:1
	v_add_f32_dpp v75, v75, v75 quad_perm:[2,3,0,1] row_mask:0xf bank_mask:0xf bound_ctrl:1
	ds_read_b32 v33, v82 offset:32000
	v_add_f32_dpp v76, v74, v74 row_half_mirror row_mask:0xf bank_mask:0xf bound_ctrl:1
	v_add_f32_dpp v64, v75, v75 row_half_mirror row_mask:0xf bank_mask:0xf bound_ctrl:1
	s_nop 0
	v_mov_b32_dpp v77, v76 row_ror:8 row_mask:0xf bank_mask:0xf bound_ctrl:1
	s_waitcnt lgkmcnt(9)
	v_pk_mul_f32 v[66:67], v[76:77], v[56:57] op_sel_hi:[1,0]
	v_pk_mul_f32 v[68:69], v[76:77], v[56:57] op_sel:[0,1]
	v_pk_mul_f32 v[70:71], v[76:77], v[58:59] op_sel_hi:[1,0]
	v_pk_mul_f32 v[72:73], v[76:77], v[58:59] op_sel:[0,1]
	v_pk_fma_f32 v[66:67], v[60:61], v[52:53], v[66:67] op_sel_hi:[1,0,1]
	v_pk_fma_f32 v[68:69], v[60:61], v[52:53], v[68:69] op_sel:[0,1,0]
	v_pk_fma_f32 v[70:71], v[60:61], v[54:55], v[70:71] op_sel_hi:[1,0,1]
	v_pk_fma_f32 v[72:73], v[60:61], v[54:55], v[72:73] op_sel:[0,1,0]
	v_pk_fma_f32 v[0:1], v[0:1], v[48:49], v[66:67] op_sel_hi:[1,0,1]
	v_pk_fma_f32 v[2:3], v[2:3], v[48:49], v[68:69] op_sel:[0,1,0]
	v_pk_fma_f32 v[4:5], v[4:5], v[50:51], v[70:71] op_sel_hi:[1,0,1]
	v_pk_fma_f32 v[6:7], v[6:7], v[50:51], v[72:73] op_sel:[0,1,0]
	ds_write_b32 v84, v64 offset:2432
	ds_write_b32 v84, v76 offset:14720
	s_waitcnt lgkmcnt(7)
	v_pk_mul_f32 v[8:9], v[0:1], v[12:13] op_sel_hi:[1,0]
	v_pk_mul_f32 v[10:11], v[0:1], v[16:17] op_sel_hi:[1,0]
	ds_read_b128 v[40:43], v80 offset:33024
	v_pk_fma_f32 v[8:9], v[2:3], v[12:13], v[8:9] op_sel:[0,1,0]
	v_pk_fma_f32 v[10:11], v[2:3], v[16:17], v[10:11] op_sel:[0,1,0]
	ds_read_b128 v[44:47], v80 offset:32256
	v_pk_fma_f32 v[8:9], v[4:5], v[14:15], v[8:9] op_sel_hi:[1,0,1]
	v_pk_fma_f32 v[10:11], v[4:5], v[18:19], v[10:11] op_sel_hi:[1,0,1]
	ds_read_b128 v[48:51], v80 offset:32512
	v_pk_fma_f32 v[8:9], v[6:7], v[14:15], v[8:9] op_sel:[0,1,0]
	v_pk_fma_f32 v[10:11], v[6:7], v[18:19], v[10:11] op_sel:[0,1,0]
	ds_read_b128 v[52:55], v80 offset:32768
	v_add_f32_dpp v74, v9, v8 row_ror:8 row_mask:0xf bank_mask:0xf bound_ctrl:1
	v_add_f32_dpp v75, v11, v10 row_ror:8 row_mask:0xf bank_mask:0xf bound_ctrl:1
	ds_read_b128 v[56:59], v80 offset:33280
	v_add_f32_dpp v74, v74, v74 quad_perm:[1,0,3,2] row_mask:0xf bank_mask:0xf bound_ctrl:1
	v_add_f32_dpp v75, v75, v75 quad_perm:[1,0,3,2] row_mask:0xf bank_mask:0xf bound_ctrl:1
	ds_read_b32 v60, v81 offset:33536
	v_add_f32_dpp v74, v74, v74 quad_perm:[2,3,0,1] row_mask:0xf bank_mask:0xf bound_ctrl:1
	v_add_f32_dpp v75, v75, v75 quad_perm:[2,3,0,1] row_mask:0xf bank_mask:0xf bound_ctrl:1
	ds_read_b32 v61, v82 offset:33536
	v_add_f32_dpp v76, v74, v74 row_half_mirror row_mask:0xf bank_mask:0xf bound_ctrl:1
	v_add_f32_dpp v36, v75, v75 row_half_mirror row_mask:0xf bank_mask:0xf bound_ctrl:1
	s_nop 0
	v_mov_b32_dpp v77, v76 row_ror:8 row_mask:0xf bank_mask:0xf bound_ctrl:1
	s_waitcnt lgkmcnt(9)
	v_pk_mul_f32 v[66:67], v[76:77], v[28:29] op_sel_hi:[1,0]
	v_pk_mul_f32 v[68:69], v[76:77], v[28:29] op_sel:[0,1]
	v_pk_mul_f32 v[70:71], v[76:77], v[30:31] op_sel_hi:[1,0]
	v_pk_mul_f32 v[72:73], v[76:77], v[30:31] op_sel:[0,1]
	v_pk_fma_f32 v[66:67], v[32:33], v[24:25], v[66:67] op_sel_hi:[1,0,1]
	v_pk_fma_f32 v[68:69], v[32:33], v[24:25], v[68:69] op_sel:[0,1,0]
	v_pk_fma_f32 v[70:71], v[32:33], v[26:27], v[70:71] op_sel_hi:[1,0,1]
	v_pk_fma_f32 v[72:73], v[32:33], v[26:27], v[72:73] op_sel:[0,1,0]
	v_pk_fma_f32 v[0:1], v[0:1], v[20:21], v[66:67] op_sel_hi:[1,0,1]
	v_pk_fma_f32 v[2:3], v[2:3], v[20:21], v[68:69] op_sel:[0,1,0]
	v_pk_fma_f32 v[4:5], v[4:5], v[22:23], v[70:71] op_sel_hi:[1,0,1]
	v_pk_fma_f32 v[6:7], v[6:7], v[22:23], v[72:73] op_sel:[0,1,0]
	ds_write_b32 v84, v36 offset:2560
	ds_write_b32 v84, v76 offset:14848
	s_waitcnt lgkmcnt(7)
	v_pk_mul_f32 v[8:9], v[0:1], v[40:41] op_sel_hi:[1,0]
	v_pk_mul_f32 v[10:11], v[0:1], v[44:45] op_sel_hi:[1,0]
	ds_read_b128 v[12:15], v80 offset:34560
	v_pk_fma_f32 v[8:9], v[2:3], v[40:41], v[8:9] op_sel:[0,1,0]
	v_pk_fma_f32 v[10:11], v[2:3], v[44:45], v[10:11] op_sel:[0,1,0]
	ds_read_b128 v[16:19], v80 offset:33792
	v_pk_fma_f32 v[8:9], v[4:5], v[42:43], v[8:9] op_sel_hi:[1,0,1]
	v_pk_fma_f32 v[10:11], v[4:5], v[46:47], v[10:11] op_sel_hi:[1,0,1]
	ds_read_b128 v[20:23], v80 offset:34048
	v_pk_fma_f32 v[8:9], v[6:7], v[42:43], v[8:9] op_sel:[0,1,0]
	v_pk_fma_f32 v[10:11], v[6:7], v[46:47], v[10:11] op_sel:[0,1,0]
	ds_read_b128 v[24:27], v80 offset:34304
	v_add_f32_dpp v74, v9, v8 row_ror:8 row_mask:0xf bank_mask:0xf bound_ctrl:1
	v_add_f32_dpp v75, v11, v10 row_ror:8 row_mask:0xf bank_mask:0xf bound_ctrl:1
	ds_read_b128 v[28:31], v80 offset:34816
	v_add_f32_dpp v74, v74, v74 quad_perm:[1,0,3,2] row_mask:0xf bank_mask:0xf bound_ctrl:1
	v_add_f32_dpp v75, v75, v75 quad_perm:[1,0,3,2] row_mask:0xf bank_mask:0xf bound_ctrl:1
	ds_read_b32 v32, v81 offset:35072
	v_add_f32_dpp v74, v74, v74 quad_perm:[2,3,0,1] row_mask:0xf bank_mask:0xf bound_ctrl:1
	v_add_f32_dpp v75, v75, v75 quad_perm:[2,3,0,1] row_mask:0xf bank_mask:0xf bound_ctrl:1
	ds_read_b32 v33, v82 offset:35072
	v_add_f32_dpp v76, v74, v74 row_half_mirror row_mask:0xf bank_mask:0xf bound_ctrl:1
	v_add_f32_dpp v64, v75, v75 row_half_mirror row_mask:0xf bank_mask:0xf bound_ctrl:1
	s_nop 0
	v_mov_b32_dpp v77, v76 row_ror:8 row_mask:0xf bank_mask:0xf bound_ctrl:1
	s_waitcnt lgkmcnt(9)
	v_pk_mul_f32 v[66:67], v[76:77], v[56:57] op_sel_hi:[1,0]
	v_pk_mul_f32 v[68:69], v[76:77], v[56:57] op_sel:[0,1]
	v_pk_mul_f32 v[70:71], v[76:77], v[58:59] op_sel_hi:[1,0]
	v_pk_mul_f32 v[72:73], v[76:77], v[58:59] op_sel:[0,1]
	v_pk_fma_f32 v[66:67], v[60:61], v[52:53], v[66:67] op_sel_hi:[1,0,1]
	v_pk_fma_f32 v[68:69], v[60:61], v[52:53], v[68:69] op_sel:[0,1,0]
	v_pk_fma_f32 v[70:71], v[60:61], v[54:55], v[70:71] op_sel_hi:[1,0,1]
	v_pk_fma_f32 v[72:73], v[60:61], v[54:55], v[72:73] op_sel:[0,1,0]
	v_pk_fma_f32 v[0:1], v[0:1], v[48:49], v[66:67] op_sel_hi:[1,0,1]
	v_pk_fma_f32 v[2:3], v[2:3], v[48:49], v[68:69] op_sel:[0,1,0]
	v_pk_fma_f32 v[4:5], v[4:5], v[50:51], v[70:71] op_sel_hi:[1,0,1]
	v_pk_fma_f32 v[6:7], v[6:7], v[50:51], v[72:73] op_sel:[0,1,0]
	ds_write_b32 v84, v64 offset:2688
	ds_write_b32 v84, v76 offset:14976
	s_waitcnt lgkmcnt(7)
	v_pk_mul_f32 v[8:9], v[0:1], v[12:13] op_sel_hi:[1,0]
	v_pk_mul_f32 v[10:11], v[0:1], v[16:17] op_sel_hi:[1,0]
	ds_read_b128 v[40:43], v80 offset:36096
	v_pk_fma_f32 v[8:9], v[2:3], v[12:13], v[8:9] op_sel:[0,1,0]
	v_pk_fma_f32 v[10:11], v[2:3], v[16:17], v[10:11] op_sel:[0,1,0]
	ds_read_b128 v[44:47], v80 offset:35328
	v_pk_fma_f32 v[8:9], v[4:5], v[14:15], v[8:9] op_sel_hi:[1,0,1]
	v_pk_fma_f32 v[10:11], v[4:5], v[18:19], v[10:11] op_sel_hi:[1,0,1]
	ds_read_b128 v[48:51], v80 offset:35584
	v_pk_fma_f32 v[8:9], v[6:7], v[14:15], v[8:9] op_sel:[0,1,0]
	v_pk_fma_f32 v[10:11], v[6:7], v[18:19], v[10:11] op_sel:[0,1,0]
	ds_read_b128 v[52:55], v80 offset:35840
	v_add_f32_dpp v74, v9, v8 row_ror:8 row_mask:0xf bank_mask:0xf bound_ctrl:1
	v_add_f32_dpp v75, v11, v10 row_ror:8 row_mask:0xf bank_mask:0xf bound_ctrl:1
	ds_read_b128 v[56:59], v80 offset:36352
	v_add_f32_dpp v74, v74, v74 quad_perm:[1,0,3,2] row_mask:0xf bank_mask:0xf bound_ctrl:1
	v_add_f32_dpp v75, v75, v75 quad_perm:[1,0,3,2] row_mask:0xf bank_mask:0xf bound_ctrl:1
	ds_read_b32 v60, v81 offset:36608
	v_add_f32_dpp v74, v74, v74 quad_perm:[2,3,0,1] row_mask:0xf bank_mask:0xf bound_ctrl:1
	v_add_f32_dpp v75, v75, v75 quad_perm:[2,3,0,1] row_mask:0xf bank_mask:0xf bound_ctrl:1
	ds_read_b32 v61, v82 offset:36608
	v_add_f32_dpp v76, v74, v74 row_half_mirror row_mask:0xf bank_mask:0xf bound_ctrl:1
	v_add_f32_dpp v36, v75, v75 row_half_mirror row_mask:0xf bank_mask:0xf bound_ctrl:1
	s_nop 0
	v_mov_b32_dpp v77, v76 row_ror:8 row_mask:0xf bank_mask:0xf bound_ctrl:1
	s_waitcnt lgkmcnt(9)
	v_pk_mul_f32 v[66:67], v[76:77], v[28:29] op_sel_hi:[1,0]
	v_pk_mul_f32 v[68:69], v[76:77], v[28:29] op_sel:[0,1]
	v_pk_mul_f32 v[70:71], v[76:77], v[30:31] op_sel_hi:[1,0]
	v_pk_mul_f32 v[72:73], v[76:77], v[30:31] op_sel:[0,1]
	v_pk_fma_f32 v[66:67], v[32:33], v[24:25], v[66:67] op_sel_hi:[1,0,1]
	v_pk_fma_f32 v[68:69], v[32:33], v[24:25], v[68:69] op_sel:[0,1,0]
	v_pk_fma_f32 v[70:71], v[32:33], v[26:27], v[70:71] op_sel_hi:[1,0,1]
	v_pk_fma_f32 v[72:73], v[32:33], v[26:27], v[72:73] op_sel:[0,1,0]
	v_pk_fma_f32 v[0:1], v[0:1], v[20:21], v[66:67] op_sel_hi:[1,0,1]
	v_pk_fma_f32 v[2:3], v[2:3], v[20:21], v[68:69] op_sel:[0,1,0]
	v_pk_fma_f32 v[4:5], v[4:5], v[22:23], v[70:71] op_sel_hi:[1,0,1]
	v_pk_fma_f32 v[6:7], v[6:7], v[22:23], v[72:73] op_sel:[0,1,0]
	ds_write_b32 v84, v36 offset:2816
	ds_write_b32 v84, v76 offset:15104
	s_waitcnt lgkmcnt(7)
	v_pk_mul_f32 v[8:9], v[0:1], v[40:41] op_sel_hi:[1,0]
	v_pk_mul_f32 v[10:11], v[0:1], v[44:45] op_sel_hi:[1,0]
	ds_read_b128 v[12:15], v80 offset:37632
	v_pk_fma_f32 v[8:9], v[2:3], v[40:41], v[8:9] op_sel:[0,1,0]
	v_pk_fma_f32 v[10:11], v[2:3], v[44:45], v[10:11] op_sel:[0,1,0]
	ds_read_b128 v[16:19], v80 offset:36864
	v_pk_fma_f32 v[8:9], v[4:5], v[42:43], v[8:9] op_sel_hi:[1,0,1]
	v_pk_fma_f32 v[10:11], v[4:5], v[46:47], v[10:11] op_sel_hi:[1,0,1]
	ds_read_b128 v[20:23], v80 offset:37120
	v_pk_fma_f32 v[8:9], v[6:7], v[42:43], v[8:9] op_sel:[0,1,0]
	v_pk_fma_f32 v[10:11], v[6:7], v[46:47], v[10:11] op_sel:[0,1,0]
	ds_read_b128 v[24:27], v80 offset:37376
	v_add_f32_dpp v74, v9, v8 row_ror:8 row_mask:0xf bank_mask:0xf bound_ctrl:1
	v_add_f32_dpp v75, v11, v10 row_ror:8 row_mask:0xf bank_mask:0xf bound_ctrl:1
	ds_read_b128 v[28:31], v80 offset:37888
	v_add_f32_dpp v74, v74, v74 quad_perm:[1,0,3,2] row_mask:0xf bank_mask:0xf bound_ctrl:1
	v_add_f32_dpp v75, v75, v75 quad_perm:[1,0,3,2] row_mask:0xf bank_mask:0xf bound_ctrl:1
	ds_read_b32 v32, v81 offset:38144
	v_add_f32_dpp v74, v74, v74 quad_perm:[2,3,0,1] row_mask:0xf bank_mask:0xf bound_ctrl:1
	v_add_f32_dpp v75, v75, v75 quad_perm:[2,3,0,1] row_mask:0xf bank_mask:0xf bound_ctrl:1
	ds_read_b32 v33, v82 offset:38144
	v_add_f32_dpp v76, v74, v74 row_half_mirror row_mask:0xf bank_mask:0xf bound_ctrl:1
	v_add_f32_dpp v64, v75, v75 row_half_mirror row_mask:0xf bank_mask:0xf bound_ctrl:1
	s_nop 0
	v_mov_b32_dpp v77, v76 row_ror:8 row_mask:0xf bank_mask:0xf bound_ctrl:1
	s_waitcnt lgkmcnt(9)
	v_pk_mul_f32 v[66:67], v[76:77], v[56:57] op_sel_hi:[1,0]
	v_pk_mul_f32 v[68:69], v[76:77], v[56:57] op_sel:[0,1]
	v_pk_mul_f32 v[70:71], v[76:77], v[58:59] op_sel_hi:[1,0]
	v_pk_mul_f32 v[72:73], v[76:77], v[58:59] op_sel:[0,1]
	v_pk_fma_f32 v[66:67], v[60:61], v[52:53], v[66:67] op_sel_hi:[1,0,1]
	v_pk_fma_f32 v[68:69], v[60:61], v[52:53], v[68:69] op_sel:[0,1,0]
	v_pk_fma_f32 v[70:71], v[60:61], v[54:55], v[70:71] op_sel_hi:[1,0,1]
	v_pk_fma_f32 v[72:73], v[60:61], v[54:55], v[72:73] op_sel:[0,1,0]
	v_pk_fma_f32 v[0:1], v[0:1], v[48:49], v[66:67] op_sel_hi:[1,0,1]
	v_pk_fma_f32 v[2:3], v[2:3], v[48:49], v[68:69] op_sel:[0,1,0]
	v_pk_fma_f32 v[4:5], v[4:5], v[50:51], v[70:71] op_sel_hi:[1,0,1]
	v_pk_fma_f32 v[6:7], v[6:7], v[50:51], v[72:73] op_sel:[0,1,0]
	ds_write_b32 v84, v64 offset:2944
	ds_write_b32 v84, v76 offset:15232
	s_waitcnt lgkmcnt(7)
	v_pk_mul_f32 v[8:9], v[0:1], v[12:13] op_sel_hi:[1,0]
	v_pk_mul_f32 v[10:11], v[0:1], v[16:17] op_sel_hi:[1,0]
	ds_read_b128 v[40:43], v80 offset:39168
	v_pk_fma_f32 v[8:9], v[2:3], v[12:13], v[8:9] op_sel:[0,1,0]
	v_pk_fma_f32 v[10:11], v[2:3], v[16:17], v[10:11] op_sel:[0,1,0]
	ds_read_b128 v[44:47], v80 offset:38400
	v_pk_fma_f32 v[8:9], v[4:5], v[14:15], v[8:9] op_sel_hi:[1,0,1]
	v_pk_fma_f32 v[10:11], v[4:5], v[18:19], v[10:11] op_sel_hi:[1,0,1]
	ds_read_b128 v[48:51], v80 offset:38656
	v_pk_fma_f32 v[8:9], v[6:7], v[14:15], v[8:9] op_sel:[0,1,0]
	v_pk_fma_f32 v[10:11], v[6:7], v[18:19], v[10:11] op_sel:[0,1,0]
	ds_read_b128 v[52:55], v80 offset:38912
	v_add_f32_dpp v74, v9, v8 row_ror:8 row_mask:0xf bank_mask:0xf bound_ctrl:1
	v_add_f32_dpp v75, v11, v10 row_ror:8 row_mask:0xf bank_mask:0xf bound_ctrl:1
	ds_read_b128 v[56:59], v80 offset:39424
	v_add_f32_dpp v74, v74, v74 quad_perm:[1,0,3,2] row_mask:0xf bank_mask:0xf bound_ctrl:1
	v_add_f32_dpp v75, v75, v75 quad_perm:[1,0,3,2] row_mask:0xf bank_mask:0xf bound_ctrl:1
	ds_read_b32 v60, v81 offset:39680
	v_add_f32_dpp v74, v74, v74 quad_perm:[2,3,0,1] row_mask:0xf bank_mask:0xf bound_ctrl:1
	v_add_f32_dpp v75, v75, v75 quad_perm:[2,3,0,1] row_mask:0xf bank_mask:0xf bound_ctrl:1
	ds_read_b32 v61, v82 offset:39680
	v_add_f32_dpp v76, v74, v74 row_half_mirror row_mask:0xf bank_mask:0xf bound_ctrl:1
	v_add_f32_dpp v36, v75, v75 row_half_mirror row_mask:0xf bank_mask:0xf bound_ctrl:1
	s_nop 0
	v_mov_b32_dpp v77, v76 row_ror:8 row_mask:0xf bank_mask:0xf bound_ctrl:1
	s_waitcnt lgkmcnt(9)
	v_pk_mul_f32 v[66:67], v[76:77], v[28:29] op_sel_hi:[1,0]
	v_pk_mul_f32 v[68:69], v[76:77], v[28:29] op_sel:[0,1]
	v_pk_mul_f32 v[70:71], v[76:77], v[30:31] op_sel_hi:[1,0]
	v_pk_mul_f32 v[72:73], v[76:77], v[30:31] op_sel:[0,1]
	v_pk_fma_f32 v[66:67], v[32:33], v[24:25], v[66:67] op_sel_hi:[1,0,1]
	v_pk_fma_f32 v[68:69], v[32:33], v[24:25], v[68:69] op_sel:[0,1,0]
	v_pk_fma_f32 v[70:71], v[32:33], v[26:27], v[70:71] op_sel_hi:[1,0,1]
	v_pk_fma_f32 v[72:73], v[32:33], v[26:27], v[72:73] op_sel:[0,1,0]
	v_pk_fma_f32 v[0:1], v[0:1], v[20:21], v[66:67] op_sel_hi:[1,0,1]
	v_pk_fma_f32 v[2:3], v[2:3], v[20:21], v[68:69] op_sel:[0,1,0]
	v_pk_fma_f32 v[4:5], v[4:5], v[22:23], v[70:71] op_sel_hi:[1,0,1]
	v_pk_fma_f32 v[6:7], v[6:7], v[22:23], v[72:73] op_sel:[0,1,0]
	ds_write_b32 v84, v36 offset:3072
	ds_write_b32 v84, v76 offset:15360
	s_waitcnt lgkmcnt(7)
	v_pk_mul_f32 v[8:9], v[0:1], v[40:41] op_sel_hi:[1,0]
	v_pk_mul_f32 v[10:11], v[0:1], v[44:45] op_sel_hi:[1,0]
	ds_read_b128 v[12:15], v80 offset:40704
	v_pk_fma_f32 v[8:9], v[2:3], v[40:41], v[8:9] op_sel:[0,1,0]
	v_pk_fma_f32 v[10:11], v[2:3], v[44:45], v[10:11] op_sel:[0,1,0]
	ds_read_b128 v[16:19], v80 offset:39936
	v_pk_fma_f32 v[8:9], v[4:5], v[42:43], v[8:9] op_sel_hi:[1,0,1]
	v_pk_fma_f32 v[10:11], v[4:5], v[46:47], v[10:11] op_sel_hi:[1,0,1]
	ds_read_b128 v[20:23], v80 offset:40192
	v_pk_fma_f32 v[8:9], v[6:7], v[42:43], v[8:9] op_sel:[0,1,0]
	v_pk_fma_f32 v[10:11], v[6:7], v[46:47], v[10:11] op_sel:[0,1,0]
	ds_read_b128 v[24:27], v80 offset:40448
	v_add_f32_dpp v74, v9, v8 row_ror:8 row_mask:0xf bank_mask:0xf bound_ctrl:1
	v_add_f32_dpp v75, v11, v10 row_ror:8 row_mask:0xf bank_mask:0xf bound_ctrl:1
	ds_read_b128 v[28:31], v80 offset:40960
	v_add_f32_dpp v74, v74, v74 quad_perm:[1,0,3,2] row_mask:0xf bank_mask:0xf bound_ctrl:1
	v_add_f32_dpp v75, v75, v75 quad_perm:[1,0,3,2] row_mask:0xf bank_mask:0xf bound_ctrl:1
	ds_read_b32 v32, v81 offset:41216
	v_add_f32_dpp v74, v74, v74 quad_perm:[2,3,0,1] row_mask:0xf bank_mask:0xf bound_ctrl:1
	v_add_f32_dpp v75, v75, v75 quad_perm:[2,3,0,1] row_mask:0xf bank_mask:0xf bound_ctrl:1
	ds_read_b32 v33, v82 offset:41216
	v_add_f32_dpp v76, v74, v74 row_half_mirror row_mask:0xf bank_mask:0xf bound_ctrl:1
	v_add_f32_dpp v64, v75, v75 row_half_mirror row_mask:0xf bank_mask:0xf bound_ctrl:1
	s_nop 0
	v_mov_b32_dpp v77, v76 row_ror:8 row_mask:0xf bank_mask:0xf bound_ctrl:1
	s_waitcnt lgkmcnt(9)
	v_pk_mul_f32 v[66:67], v[76:77], v[56:57] op_sel_hi:[1,0]
	v_pk_mul_f32 v[68:69], v[76:77], v[56:57] op_sel:[0,1]
	v_pk_mul_f32 v[70:71], v[76:77], v[58:59] op_sel_hi:[1,0]
	v_pk_mul_f32 v[72:73], v[76:77], v[58:59] op_sel:[0,1]
	v_pk_fma_f32 v[66:67], v[60:61], v[52:53], v[66:67] op_sel_hi:[1,0,1]
	v_pk_fma_f32 v[68:69], v[60:61], v[52:53], v[68:69] op_sel:[0,1,0]
	v_pk_fma_f32 v[70:71], v[60:61], v[54:55], v[70:71] op_sel_hi:[1,0,1]
	v_pk_fma_f32 v[72:73], v[60:61], v[54:55], v[72:73] op_sel:[0,1,0]
	v_pk_fma_f32 v[0:1], v[0:1], v[48:49], v[66:67] op_sel_hi:[1,0,1]
	v_pk_fma_f32 v[2:3], v[2:3], v[48:49], v[68:69] op_sel:[0,1,0]
	v_pk_fma_f32 v[4:5], v[4:5], v[50:51], v[70:71] op_sel_hi:[1,0,1]
	v_pk_fma_f32 v[6:7], v[6:7], v[50:51], v[72:73] op_sel:[0,1,0]
	ds_write_b32 v84, v64 offset:3200
	ds_write_b32 v84, v76 offset:15488
	s_waitcnt lgkmcnt(7)
	v_pk_mul_f32 v[8:9], v[0:1], v[12:13] op_sel_hi:[1,0]
	v_pk_mul_f32 v[10:11], v[0:1], v[16:17] op_sel_hi:[1,0]
	ds_read_b128 v[40:43], v80 offset:42240
	v_pk_fma_f32 v[8:9], v[2:3], v[12:13], v[8:9] op_sel:[0,1,0]
	v_pk_fma_f32 v[10:11], v[2:3], v[16:17], v[10:11] op_sel:[0,1,0]
	ds_read_b128 v[44:47], v80 offset:41472
	v_pk_fma_f32 v[8:9], v[4:5], v[14:15], v[8:9] op_sel_hi:[1,0,1]
	v_pk_fma_f32 v[10:11], v[4:5], v[18:19], v[10:11] op_sel_hi:[1,0,1]
	ds_read_b128 v[48:51], v80 offset:41728
	v_pk_fma_f32 v[8:9], v[6:7], v[14:15], v[8:9] op_sel:[0,1,0]
	v_pk_fma_f32 v[10:11], v[6:7], v[18:19], v[10:11] op_sel:[0,1,0]
	ds_read_b128 v[52:55], v80 offset:41984
	v_add_f32_dpp v74, v9, v8 row_ror:8 row_mask:0xf bank_mask:0xf bound_ctrl:1
	v_add_f32_dpp v75, v11, v10 row_ror:8 row_mask:0xf bank_mask:0xf bound_ctrl:1
	ds_read_b128 v[56:59], v80 offset:42496
	v_add_f32_dpp v74, v74, v74 quad_perm:[1,0,3,2] row_mask:0xf bank_mask:0xf bound_ctrl:1
	v_add_f32_dpp v75, v75, v75 quad_perm:[1,0,3,2] row_mask:0xf bank_mask:0xf bound_ctrl:1
	ds_read_b32 v60, v81 offset:42752
	v_add_f32_dpp v74, v74, v74 quad_perm:[2,3,0,1] row_mask:0xf bank_mask:0xf bound_ctrl:1
	v_add_f32_dpp v75, v75, v75 quad_perm:[2,3,0,1] row_mask:0xf bank_mask:0xf bound_ctrl:1
	ds_read_b32 v61, v82 offset:42752
	v_add_f32_dpp v76, v74, v74 row_half_mirror row_mask:0xf bank_mask:0xf bound_ctrl:1
	v_add_f32_dpp v36, v75, v75 row_half_mirror row_mask:0xf bank_mask:0xf bound_ctrl:1
	s_nop 0
	v_mov_b32_dpp v77, v76 row_ror:8 row_mask:0xf bank_mask:0xf bound_ctrl:1
	s_waitcnt lgkmcnt(9)
	v_pk_mul_f32 v[66:67], v[76:77], v[28:29] op_sel_hi:[1,0]
	v_pk_mul_f32 v[68:69], v[76:77], v[28:29] op_sel:[0,1]
	v_pk_mul_f32 v[70:71], v[76:77], v[30:31] op_sel_hi:[1,0]
	v_pk_mul_f32 v[72:73], v[76:77], v[30:31] op_sel:[0,1]
	v_pk_fma_f32 v[66:67], v[32:33], v[24:25], v[66:67] op_sel_hi:[1,0,1]
	v_pk_fma_f32 v[68:69], v[32:33], v[24:25], v[68:69] op_sel:[0,1,0]
	v_pk_fma_f32 v[70:71], v[32:33], v[26:27], v[70:71] op_sel_hi:[1,0,1]
	v_pk_fma_f32 v[72:73], v[32:33], v[26:27], v[72:73] op_sel:[0,1,0]
	v_pk_fma_f32 v[0:1], v[0:1], v[20:21], v[66:67] op_sel_hi:[1,0,1]
	v_pk_fma_f32 v[2:3], v[2:3], v[20:21], v[68:69] op_sel:[0,1,0]
	v_pk_fma_f32 v[4:5], v[4:5], v[22:23], v[70:71] op_sel_hi:[1,0,1]
	v_pk_fma_f32 v[6:7], v[6:7], v[22:23], v[72:73] op_sel:[0,1,0]
	ds_write_b32 v84, v36 offset:3328
	ds_write_b32 v84, v76 offset:15616
	s_waitcnt lgkmcnt(7)
	v_pk_mul_f32 v[8:9], v[0:1], v[40:41] op_sel_hi:[1,0]
	v_pk_mul_f32 v[10:11], v[0:1], v[44:45] op_sel_hi:[1,0]
	ds_read_b128 v[12:15], v80 offset:43776
	v_pk_fma_f32 v[8:9], v[2:3], v[40:41], v[8:9] op_sel:[0,1,0]
	v_pk_fma_f32 v[10:11], v[2:3], v[44:45], v[10:11] op_sel:[0,1,0]
	ds_read_b128 v[16:19], v80 offset:43008
	v_pk_fma_f32 v[8:9], v[4:5], v[42:43], v[8:9] op_sel_hi:[1,0,1]
	v_pk_fma_f32 v[10:11], v[4:5], v[46:47], v[10:11] op_sel_hi:[1,0,1]
	ds_read_b128 v[20:23], v80 offset:43264
	v_pk_fma_f32 v[8:9], v[6:7], v[42:43], v[8:9] op_sel:[0,1,0]
	v_pk_fma_f32 v[10:11], v[6:7], v[46:47], v[10:11] op_sel:[0,1,0]
	ds_read_b128 v[24:27], v80 offset:43520
	v_add_f32_dpp v74, v9, v8 row_ror:8 row_mask:0xf bank_mask:0xf bound_ctrl:1
	v_add_f32_dpp v75, v11, v10 row_ror:8 row_mask:0xf bank_mask:0xf bound_ctrl:1
	ds_read_b128 v[28:31], v80 offset:44032
	v_add_f32_dpp v74, v74, v74 quad_perm:[1,0,3,2] row_mask:0xf bank_mask:0xf bound_ctrl:1
	v_add_f32_dpp v75, v75, v75 quad_perm:[1,0,3,2] row_mask:0xf bank_mask:0xf bound_ctrl:1
	ds_read_b32 v32, v81 offset:44288
	v_add_f32_dpp v74, v74, v74 quad_perm:[2,3,0,1] row_mask:0xf bank_mask:0xf bound_ctrl:1
	v_add_f32_dpp v75, v75, v75 quad_perm:[2,3,0,1] row_mask:0xf bank_mask:0xf bound_ctrl:1
	ds_read_b32 v33, v82 offset:44288
	v_add_f32_dpp v76, v74, v74 row_half_mirror row_mask:0xf bank_mask:0xf bound_ctrl:1
	v_add_f32_dpp v64, v75, v75 row_half_mirror row_mask:0xf bank_mask:0xf bound_ctrl:1
	s_nop 0
	v_mov_b32_dpp v77, v76 row_ror:8 row_mask:0xf bank_mask:0xf bound_ctrl:1
	s_waitcnt lgkmcnt(9)
	v_pk_mul_f32 v[66:67], v[76:77], v[56:57] op_sel_hi:[1,0]
	v_pk_mul_f32 v[68:69], v[76:77], v[56:57] op_sel:[0,1]
	v_pk_mul_f32 v[70:71], v[76:77], v[58:59] op_sel_hi:[1,0]
	v_pk_mul_f32 v[72:73], v[76:77], v[58:59] op_sel:[0,1]
	v_pk_fma_f32 v[66:67], v[60:61], v[52:53], v[66:67] op_sel_hi:[1,0,1]
	v_pk_fma_f32 v[68:69], v[60:61], v[52:53], v[68:69] op_sel:[0,1,0]
	v_pk_fma_f32 v[70:71], v[60:61], v[54:55], v[70:71] op_sel_hi:[1,0,1]
	v_pk_fma_f32 v[72:73], v[60:61], v[54:55], v[72:73] op_sel:[0,1,0]
	v_pk_fma_f32 v[0:1], v[0:1], v[48:49], v[66:67] op_sel_hi:[1,0,1]
	v_pk_fma_f32 v[2:3], v[2:3], v[48:49], v[68:69] op_sel:[0,1,0]
	v_pk_fma_f32 v[4:5], v[4:5], v[50:51], v[70:71] op_sel_hi:[1,0,1]
	v_pk_fma_f32 v[6:7], v[6:7], v[50:51], v[72:73] op_sel:[0,1,0]
	ds_write_b32 v84, v64 offset:3456
	ds_write_b32 v84, v76 offset:15744
	s_waitcnt lgkmcnt(7)
	v_pk_mul_f32 v[8:9], v[0:1], v[12:13] op_sel_hi:[1,0]
	v_pk_mul_f32 v[10:11], v[0:1], v[16:17] op_sel_hi:[1,0]
	ds_read_b128 v[40:43], v80 offset:45312
	v_pk_fma_f32 v[8:9], v[2:3], v[12:13], v[8:9] op_sel:[0,1,0]
	v_pk_fma_f32 v[10:11], v[2:3], v[16:17], v[10:11] op_sel:[0,1,0]
	ds_read_b128 v[44:47], v80 offset:44544
	v_pk_fma_f32 v[8:9], v[4:5], v[14:15], v[8:9] op_sel_hi:[1,0,1]
	v_pk_fma_f32 v[10:11], v[4:5], v[18:19], v[10:11] op_sel_hi:[1,0,1]
	ds_read_b128 v[48:51], v80 offset:44800
	v_pk_fma_f32 v[8:9], v[6:7], v[14:15], v[8:9] op_sel:[0,1,0]
	v_pk_fma_f32 v[10:11], v[6:7], v[18:19], v[10:11] op_sel:[0,1,0]
	ds_read_b128 v[52:55], v80 offset:45056
	v_add_f32_dpp v74, v9, v8 row_ror:8 row_mask:0xf bank_mask:0xf bound_ctrl:1
	v_add_f32_dpp v75, v11, v10 row_ror:8 row_mask:0xf bank_mask:0xf bound_ctrl:1
	ds_read_b128 v[56:59], v80 offset:45568
	v_add_f32_dpp v74, v74, v74 quad_perm:[1,0,3,2] row_mask:0xf bank_mask:0xf bound_ctrl:1
	v_add_f32_dpp v75, v75, v75 quad_perm:[1,0,3,2] row_mask:0xf bank_mask:0xf bound_ctrl:1
	ds_read_b32 v60, v81 offset:45824
	v_add_f32_dpp v74, v74, v74 quad_perm:[2,3,0,1] row_mask:0xf bank_mask:0xf bound_ctrl:1
	v_add_f32_dpp v75, v75, v75 quad_perm:[2,3,0,1] row_mask:0xf bank_mask:0xf bound_ctrl:1
	ds_read_b32 v61, v82 offset:45824
	v_add_f32_dpp v76, v74, v74 row_half_mirror row_mask:0xf bank_mask:0xf bound_ctrl:1
	v_add_f32_dpp v36, v75, v75 row_half_mirror row_mask:0xf bank_mask:0xf bound_ctrl:1
	s_nop 0
	v_mov_b32_dpp v77, v76 row_ror:8 row_mask:0xf bank_mask:0xf bound_ctrl:1
	s_waitcnt lgkmcnt(9)
	v_pk_mul_f32 v[66:67], v[76:77], v[28:29] op_sel_hi:[1,0]
	v_pk_mul_f32 v[68:69], v[76:77], v[28:29] op_sel:[0,1]
	v_pk_mul_f32 v[70:71], v[76:77], v[30:31] op_sel_hi:[1,0]
	v_pk_mul_f32 v[72:73], v[76:77], v[30:31] op_sel:[0,1]
	v_pk_fma_f32 v[66:67], v[32:33], v[24:25], v[66:67] op_sel_hi:[1,0,1]
	v_pk_fma_f32 v[68:69], v[32:33], v[24:25], v[68:69] op_sel:[0,1,0]
	v_pk_fma_f32 v[70:71], v[32:33], v[26:27], v[70:71] op_sel_hi:[1,0,1]
	v_pk_fma_f32 v[72:73], v[32:33], v[26:27], v[72:73] op_sel:[0,1,0]
	v_pk_fma_f32 v[0:1], v[0:1], v[20:21], v[66:67] op_sel_hi:[1,0,1]
	v_pk_fma_f32 v[2:3], v[2:3], v[20:21], v[68:69] op_sel:[0,1,0]
	v_pk_fma_f32 v[4:5], v[4:5], v[22:23], v[70:71] op_sel_hi:[1,0,1]
	v_pk_fma_f32 v[6:7], v[6:7], v[22:23], v[72:73] op_sel:[0,1,0]
	ds_write_b32 v84, v36 offset:3584
	ds_write_b32 v84, v76 offset:15872
	s_waitcnt lgkmcnt(7)
	v_pk_mul_f32 v[8:9], v[0:1], v[40:41] op_sel_hi:[1,0]
	v_pk_mul_f32 v[10:11], v[0:1], v[44:45] op_sel_hi:[1,0]
	ds_read_b128 v[12:15], v80 offset:46848
	v_pk_fma_f32 v[8:9], v[2:3], v[40:41], v[8:9] op_sel:[0,1,0]
	v_pk_fma_f32 v[10:11], v[2:3], v[44:45], v[10:11] op_sel:[0,1,0]
	ds_read_b128 v[16:19], v80 offset:46080
	v_pk_fma_f32 v[8:9], v[4:5], v[42:43], v[8:9] op_sel_hi:[1,0,1]
	v_pk_fma_f32 v[10:11], v[4:5], v[46:47], v[10:11] op_sel_hi:[1,0,1]
	ds_read_b128 v[20:23], v80 offset:46336
	v_pk_fma_f32 v[8:9], v[6:7], v[42:43], v[8:9] op_sel:[0,1,0]
	v_pk_fma_f32 v[10:11], v[6:7], v[46:47], v[10:11] op_sel:[0,1,0]
	ds_read_b128 v[24:27], v80 offset:46592
	v_add_f32_dpp v74, v9, v8 row_ror:8 row_mask:0xf bank_mask:0xf bound_ctrl:1
	v_add_f32_dpp v75, v11, v10 row_ror:8 row_mask:0xf bank_mask:0xf bound_ctrl:1
	ds_read_b128 v[28:31], v80 offset:47104
	v_add_f32_dpp v74, v74, v74 quad_perm:[1,0,3,2] row_mask:0xf bank_mask:0xf bound_ctrl:1
	v_add_f32_dpp v75, v75, v75 quad_perm:[1,0,3,2] row_mask:0xf bank_mask:0xf bound_ctrl:1
	ds_read_b32 v32, v81 offset:47360
	v_add_f32_dpp v74, v74, v74 quad_perm:[2,3,0,1] row_mask:0xf bank_mask:0xf bound_ctrl:1
	v_add_f32_dpp v75, v75, v75 quad_perm:[2,3,0,1] row_mask:0xf bank_mask:0xf bound_ctrl:1
	ds_read_b32 v33, v82 offset:47360
	v_add_f32_dpp v76, v74, v74 row_half_mirror row_mask:0xf bank_mask:0xf bound_ctrl:1
	v_add_f32_dpp v64, v75, v75 row_half_mirror row_mask:0xf bank_mask:0xf bound_ctrl:1
	s_nop 0
	v_mov_b32_dpp v77, v76 row_ror:8 row_mask:0xf bank_mask:0xf bound_ctrl:1
	s_waitcnt lgkmcnt(9)
	v_pk_mul_f32 v[66:67], v[76:77], v[56:57] op_sel_hi:[1,0]
	v_pk_mul_f32 v[68:69], v[76:77], v[56:57] op_sel:[0,1]
	v_pk_mul_f32 v[70:71], v[76:77], v[58:59] op_sel_hi:[1,0]
	v_pk_mul_f32 v[72:73], v[76:77], v[58:59] op_sel:[0,1]
	v_pk_fma_f32 v[66:67], v[60:61], v[52:53], v[66:67] op_sel_hi:[1,0,1]
	v_pk_fma_f32 v[68:69], v[60:61], v[52:53], v[68:69] op_sel:[0,1,0]
	v_pk_fma_f32 v[70:71], v[60:61], v[54:55], v[70:71] op_sel_hi:[1,0,1]
	v_pk_fma_f32 v[72:73], v[60:61], v[54:55], v[72:73] op_sel:[0,1,0]
	v_pk_fma_f32 v[0:1], v[0:1], v[48:49], v[66:67] op_sel_hi:[1,0,1]
	v_pk_fma_f32 v[2:3], v[2:3], v[48:49], v[68:69] op_sel:[0,1,0]
	v_pk_fma_f32 v[4:5], v[4:5], v[50:51], v[70:71] op_sel_hi:[1,0,1]
	v_pk_fma_f32 v[6:7], v[6:7], v[50:51], v[72:73] op_sel:[0,1,0]
	ds_write_b32 v84, v64 offset:3712
	ds_write_b32 v84, v76 offset:16000
	s_waitcnt lgkmcnt(7)
	v_pk_mul_f32 v[8:9], v[0:1], v[12:13] op_sel_hi:[1,0]
	v_pk_mul_f32 v[10:11], v[0:1], v[16:17] op_sel_hi:[1,0]
	ds_read_b128 v[40:43], v80 offset:48384
	v_pk_fma_f32 v[8:9], v[2:3], v[12:13], v[8:9] op_sel:[0,1,0]
	v_pk_fma_f32 v[10:11], v[2:3], v[16:17], v[10:11] op_sel:[0,1,0]
	ds_read_b128 v[44:47], v80 offset:47616
	v_pk_fma_f32 v[8:9], v[4:5], v[14:15], v[8:9] op_sel_hi:[1,0,1]
	v_pk_fma_f32 v[10:11], v[4:5], v[18:19], v[10:11] op_sel_hi:[1,0,1]
	ds_read_b128 v[48:51], v80 offset:47872
	v_pk_fma_f32 v[8:9], v[6:7], v[14:15], v[8:9] op_sel:[0,1,0]
	v_pk_fma_f32 v[10:11], v[6:7], v[18:19], v[10:11] op_sel:[0,1,0]
	ds_read_b128 v[52:55], v80 offset:48128
	v_add_f32_dpp v74, v9, v8 row_ror:8 row_mask:0xf bank_mask:0xf bound_ctrl:1
	v_add_f32_dpp v75, v11, v10 row_ror:8 row_mask:0xf bank_mask:0xf bound_ctrl:1
	ds_read_b128 v[56:59], v80 offset:48640
	v_add_f32_dpp v74, v74, v74 quad_perm:[1,0,3,2] row_mask:0xf bank_mask:0xf bound_ctrl:1
	v_add_f32_dpp v75, v75, v75 quad_perm:[1,0,3,2] row_mask:0xf bank_mask:0xf bound_ctrl:1
	ds_read_b32 v60, v81 offset:48896
	v_add_f32_dpp v74, v74, v74 quad_perm:[2,3,0,1] row_mask:0xf bank_mask:0xf bound_ctrl:1
	v_add_f32_dpp v75, v75, v75 quad_perm:[2,3,0,1] row_mask:0xf bank_mask:0xf bound_ctrl:1
	ds_read_b32 v61, v82 offset:48896
	v_add_f32_dpp v76, v74, v74 row_half_mirror row_mask:0xf bank_mask:0xf bound_ctrl:1
	v_add_f32_dpp v36, v75, v75 row_half_mirror row_mask:0xf bank_mask:0xf bound_ctrl:1
	s_nop 0
	v_mov_b32_dpp v77, v76 row_ror:8 row_mask:0xf bank_mask:0xf bound_ctrl:1
	s_waitcnt lgkmcnt(9)
	v_pk_mul_f32 v[66:67], v[76:77], v[28:29] op_sel_hi:[1,0]
	v_pk_mul_f32 v[68:69], v[76:77], v[28:29] op_sel:[0,1]
	v_pk_mul_f32 v[70:71], v[76:77], v[30:31] op_sel_hi:[1,0]
	v_pk_mul_f32 v[72:73], v[76:77], v[30:31] op_sel:[0,1]
	v_pk_fma_f32 v[66:67], v[32:33], v[24:25], v[66:67] op_sel_hi:[1,0,1]
	v_pk_fma_f32 v[68:69], v[32:33], v[24:25], v[68:69] op_sel:[0,1,0]
	v_pk_fma_f32 v[70:71], v[32:33], v[26:27], v[70:71] op_sel_hi:[1,0,1]
	v_pk_fma_f32 v[72:73], v[32:33], v[26:27], v[72:73] op_sel:[0,1,0]
	v_pk_fma_f32 v[0:1], v[0:1], v[20:21], v[66:67] op_sel_hi:[1,0,1]
	v_pk_fma_f32 v[2:3], v[2:3], v[20:21], v[68:69] op_sel:[0,1,0]
	v_pk_fma_f32 v[4:5], v[4:5], v[22:23], v[70:71] op_sel_hi:[1,0,1]
	v_pk_fma_f32 v[6:7], v[6:7], v[22:23], v[72:73] op_sel:[0,1,0]
	ds_write_b32 v84, v36 offset:3840
	ds_write_b32 v84, v76 offset:16128
	s_waitcnt lgkmcnt(7)
	v_pk_mul_f32 v[8:9], v[0:1], v[40:41] op_sel_hi:[1,0]
	v_pk_mul_f32 v[10:11], v[0:1], v[44:45] op_sel_hi:[1,0]
	v_pk_fma_f32 v[8:9], v[2:3], v[40:41], v[8:9] op_sel:[0,1,0]
	v_pk_fma_f32 v[10:11], v[2:3], v[44:45], v[10:11] op_sel:[0,1,0]
	v_pk_fma_f32 v[8:9], v[4:5], v[42:43], v[8:9] op_sel_hi:[1,0,1]
	v_pk_fma_f32 v[10:11], v[4:5], v[46:47], v[10:11] op_sel_hi:[1,0,1]
	v_pk_fma_f32 v[8:9], v[6:7], v[42:43], v[8:9] op_sel:[0,1,0]
	v_pk_fma_f32 v[10:11], v[6:7], v[46:47], v[10:11] op_sel:[0,1,0]
	s_nop 0
	v_add_f32_dpp v74, v9, v8 row_ror:8 row_mask:0xf bank_mask:0xf bound_ctrl:1
	v_add_f32_dpp v75, v11, v10 row_ror:8 row_mask:0xf bank_mask:0xf bound_ctrl:1
	s_nop 0
	v_add_f32_dpp v74, v74, v74 quad_perm:[1,0,3,2] row_mask:0xf bank_mask:0xf bound_ctrl:1
	v_add_f32_dpp v75, v75, v75 quad_perm:[1,0,3,2] row_mask:0xf bank_mask:0xf bound_ctrl:1
	s_nop 0
	v_add_f32_dpp v74, v74, v74 quad_perm:[2,3,0,1] row_mask:0xf bank_mask:0xf bound_ctrl:1
	v_add_f32_dpp v75, v75, v75 quad_perm:[2,3,0,1] row_mask:0xf bank_mask:0xf bound_ctrl:1
	s_nop 0
	v_add_f32_dpp v76, v74, v74 row_half_mirror row_mask:0xf bank_mask:0xf bound_ctrl:1
	v_add_f32_dpp v64, v75, v75 row_half_mirror row_mask:0xf bank_mask:0xf bound_ctrl:1
	s_nop 0
	v_mov_b32_dpp v77, v76 row_ror:8 row_mask:0xf bank_mask:0xf bound_ctrl:1
	s_waitcnt lgkmcnt(2)
	v_pk_mul_f32 v[66:67], v[76:77], v[56:57] op_sel_hi:[1,0]
	v_pk_mul_f32 v[68:69], v[76:77], v[56:57] op_sel:[0,1]
	v_pk_mul_f32 v[70:71], v[76:77], v[58:59] op_sel_hi:[1,0]
	v_pk_mul_f32 v[72:73], v[76:77], v[58:59] op_sel:[0,1]
	v_pk_fma_f32 v[66:67], v[60:61], v[52:53], v[66:67] op_sel_hi:[1,0,1]
	v_pk_fma_f32 v[68:69], v[60:61], v[52:53], v[68:69] op_sel:[0,1,0]
	v_pk_fma_f32 v[70:71], v[60:61], v[54:55], v[70:71] op_sel_hi:[1,0,1]
	v_pk_fma_f32 v[72:73], v[60:61], v[54:55], v[72:73] op_sel:[0,1,0]
	v_pk_fma_f32 v[0:1], v[0:1], v[48:49], v[66:67] op_sel_hi:[1,0,1]
	v_pk_fma_f32 v[2:3], v[2:3], v[48:49], v[68:69] op_sel:[0,1,0]
	v_pk_fma_f32 v[4:5], v[4:5], v[50:51], v[70:71] op_sel_hi:[1,0,1]
	v_pk_fma_f32 v[6:7], v[6:7], v[50:51], v[72:73] op_sel:[0,1,0]
	ds_write_b32 v84, v64 offset:3968
	ds_write_b32 v84, v76 offset:16256
